# batched RMW epilogue in resid phases + XCD-hierarchical grid barrier (one L2 writeback per XCD, per-XCC counters)
# speedup vs baseline: 1.4571x; 1.4571x over previous
; __global__ void __launch_bounds__(256, 2) hybrid_megakernel(Params p) {
;   __shared__ __attribute__((aligned(16))) char smem[SMEM_BYTES];
;   unsigned epoch = 0;
;   for (int ph = p.ph_lo; ph < p.ph_hi; ++ph) {
.LBB0_1:
	s_getreg_b32 s100, hwreg(HW_REG_XCC_ID, 0, 4)
	s_load_dwordx2 s[4:5], s[0:1], 0x280
	s_load_dwordx2 s[6:7], s[0:1], 0x250
	s_mov_b32 s101, 0
	v_and_b32_e32 v1, 0x3ff, v0
	v_mov_b32_e32 v2, 0
	v_mov_b32_e32 v3, 1
	s_and_b32 s100, s100, 15
	s_lshl_b32 s10, s100, 2
	s_add_u32 s10, s10, 32
	v_mov_b32_e32 v4, s10
	s_waitcnt lgkmcnt(0)
	v_cmp_eq_u32_e32 vcc, 0, v1
	s_and_saveexec_b64 s[8:9], vcc
	s_cbranch_execz .Lxb_census_done
	global_atomic_add v4, v3, s[4:5]
.Lxb_census_done:
	s_or_b64 exec, exec, s[8:9]
	s_cmp_lg_u32 s2, 0
	s_cbranch_scc1 .Lxb_zero_done
	v_cmp_gt_u32_e32 vcc, 64, v1
	s_and_saveexec_b64 s[8:9], vcc
	s_cbranch_execz .Lxb_zero_skip
	v_lshlrev_b32_e32 v4, 8, v1
	global_store_dword v4, v2, s[6:7] sc0 sc1
.Lxb_zero_skip:
	s_or_b64 exec, exec, s[8:9]
.Lxb_zero_done:
	s_load_dwordx16 s[4:19], s[0:1], 0x0
	s_load_dwordx16 s[36:51], s[0:1], 0x40
	s_mov_b32 s88, s2
	s_cmpk_lt_i32 s88, 0x400
	v_and_b32_e32 v224, 0x3ff, v0
	v_and_b32_e32 v0, 0x3fffffff, v0
	s_waitcnt lgkmcnt(0)
	v_writelane_b32 v253, s36, 0
	v_mbcnt_lo_u32_b32 v226, -1, 0
	s_mov_b32 s97, 0
	v_writelane_b32 v253, s37, 1
	v_writelane_b32 v253, s38, 2
	v_writelane_b32 v253, s39, 3
	v_writelane_b32 v253, s40, 4
	v_writelane_b32 v253, s41, 5
	v_writelane_b32 v253, s42, 6
	v_writelane_b32 v253, s43, 7
	v_writelane_b32 v253, s44, 8
	v_writelane_b32 v253, s45, 9
	v_writelane_b32 v253, s46, 10
	v_writelane_b32 v253, s47, 11
	v_writelane_b32 v253, s48, 12
	v_writelane_b32 v253, s49, 13
	v_writelane_b32 v253, s50, 14
	v_writelane_b32 v253, s51, 15
	s_load_dwordx16 s[36:51], s[0:1], 0x80
	v_mov_b32_e32 v189, 0
	v_mov_b32_e32 v225, 0x358637bd
	v_mbcnt_hi_u32_b32 v227, -1, v226
	v_mov_b32_e32 v228, 0xff800000
	s_waitcnt lgkmcnt(0)
	v_writelane_b32 v253, s36, 16
	v_mov_b32_e32 v229, 0x41b17218
	v_mov_b32_e32 v230, 0x80
	v_writelane_b32 v253, s37, 17
	v_writelane_b32 v253, s38, 18
	v_writelane_b32 v253, s39, 19
	v_writelane_b32 v253, s40, 20
	v_writelane_b32 v253, s41, 21
	v_writelane_b32 v253, s42, 22
	v_writelane_b32 v253, s43, 23
	v_writelane_b32 v253, s44, 24
	v_writelane_b32 v253, s45, 25
	v_writelane_b32 v253, s46, 26
	v_writelane_b32 v253, s47, 27
	v_writelane_b32 v253, s48, 28
	v_writelane_b32 v253, s49, 29
	v_writelane_b32 v253, s50, 30
	v_writelane_b32 v253, s51, 31
	s_load_dwordx16 s[36:51], s[0:1], 0xc0
	v_mov_b32_e32 v231, 0x3f80
	v_mov_b32_e32 v236, 0x9f
	v_mov_b32_e32 v222, 0x8200
	s_waitcnt lgkmcnt(0)
	v_writelane_b32 v253, s36, 32
	s_nop 1
	v_writelane_b32 v253, s37, 33
	v_writelane_b32 v253, s38, 34
	v_writelane_b32 v253, s39, 35
	v_writelane_b32 v253, s40, 36
	v_writelane_b32 v253, s41, 37
	v_writelane_b32 v253, s42, 38
	v_writelane_b32 v253, s43, 39
	v_writelane_b32 v253, s44, 40
	v_writelane_b32 v253, s45, 41
	v_writelane_b32 v253, s46, 42
	v_writelane_b32 v253, s47, 43
	v_writelane_b32 v253, s48, 44
	v_writelane_b32 v253, s49, 45
	v_writelane_b32 v253, s50, 46
	v_writelane_b32 v253, s51, 47
	s_load_dwordx16 s[36:51], s[0:1], 0x100
	s_waitcnt lgkmcnt(0)
	v_writelane_b32 v253, s36, 48
	s_nop 1
	v_writelane_b32 v253, s37, 49
	v_writelane_b32 v253, s38, 50
	v_writelane_b32 v253, s39, 51
	v_writelane_b32 v253, s40, 52
	v_writelane_b32 v253, s41, 53
	v_writelane_b32 v253, s42, 54
	v_writelane_b32 v253, s43, 55
	v_writelane_b32 v253, s44, 56
	v_writelane_b32 v253, s45, 57
	v_writelane_b32 v253, s46, 58
	v_writelane_b32 v253, s47, 59
	v_writelane_b32 v253, s48, 60
	v_writelane_b32 v253, s49, 61
	v_writelane_b32 v253, s50, 62
	v_writelane_b32 v253, s51, 63
	s_load_dwordx16 s[36:51], s[0:1], 0x140
	s_load_dwordx2 s[2:3], s[0:1], 0x180
	s_load_dwordx16 s[68:83], s[0:1], 0x198
	s_load_dwordx16 s[52:67], s[0:1], 0x1d8
	s_load_dwordx4 s[20:23], s[0:1], 0x238
	s_load_dwordx8 s[24:31], s[0:1], 0x218
	s_waitcnt lgkmcnt(0)
	v_writelane_b32 v254, s2, 0
	s_nop 1
	v_writelane_b32 v254, s3, 1
	v_writelane_b32 v254, s52, 2
	s_load_dwordx2 s[2:3], s[0:1], 0x248
	s_nop 0
	v_writelane_b32 v254, s53, 3
	v_writelane_b32 v254, s54, 4
	v_writelane_b32 v254, s55, 5
	v_writelane_b32 v254, s56, 6
	v_writelane_b32 v254, s57, 7
	v_writelane_b32 v254, s58, 8
	v_writelane_b32 v254, s59, 9
	v_writelane_b32 v254, s60, 10
	v_writelane_b32 v254, s61, 11
	v_writelane_b32 v254, s62, 12
	v_writelane_b32 v254, s63, 13
	v_writelane_b32 v254, s64, 14
	v_writelane_b32 v254, s65, 15
	v_writelane_b32 v254, s66, 16
	v_writelane_b32 v254, s67, 17
	s_waitcnt lgkmcnt(0)
; __global__ void __launch_bounds__(256, 2) hybrid_megakernel(Params p) {
;   __shared__ __attribute__((aligned(16))) char smem[SMEM_BYTES];
;   unsigned epoch = 0;
;   for (int ph = p.ph_lo; ph < p.ph_hi; ++ph) {
;     const int L = ph / NPH, s = ph % NPH;
;     if (s == 0 && L > 0) continue;
;     ...
;     if (s != ONLY) continue;
;     ...
;     switch (s) {
	v_writelane_b32 v254, s2, 18
	s_nop 1
	v_writelane_b32 v254, s3, 19
	v_writelane_b32 v254, s24, 20
	s_load_dwordx2 s[2:3], s[0:1], 0x270
	s_nop 0
	v_writelane_b32 v254, s25, 21
	v_writelane_b32 v254, s26, 22
	v_writelane_b32 v254, s27, 23
	v_writelane_b32 v254, s28, 24
	v_writelane_b32 v254, s29, 25
	v_writelane_b32 v254, s30, 26
	v_writelane_b32 v254, s31, 27
	s_load_dwordx4 s[24:27], s[0:1], 0x260
	s_waitcnt lgkmcnt(0)
	v_writelane_b32 v254, s2, 28
	s_nop 1
	v_writelane_b32 v254, s3, 29
	s_load_dwordx2 s[2:3], s[0:1], 0x280
	v_writelane_b32 v254, s24, 30
	s_nop 1
	v_writelane_b32 v254, s25, 31
	v_writelane_b32 v254, s26, 32
	v_writelane_b32 v254, s27, 33
	s_waitcnt lgkmcnt(0)
	v_writelane_b32 v254, s2, 34
	s_nop 1
	v_writelane_b32 v254, s3, 35
	s_cselect_b64 s[2:3], -1, 0
	v_writelane_b32 v254, s2, 36
	s_add_u32 s0, s0, 0x288
	s_addc_u32 s1, s1, 0
	v_writelane_b32 v254, s3, 37
	v_writelane_b32 v254, s0, 38
	s_cmpk_lt_i32 s88, 0x784
	s_mov_b32 s2, 0
	v_writelane_b32 v254, s1, 39
	s_cselect_b64 s[0:1], -1, 0
	v_writelane_b32 v254, s0, 40
	s_cmp_lg_u64 s[16:17], 0
	s_nop 0
	v_writelane_b32 v254, s1, 41
	s_cselect_b64 s[0:1], -1, 0
	v_writelane_b32 v254, s0, 42
	s_cmp_lg_u64 s[14:15], 0
	s_nop 0
	v_writelane_b32 v254, s1, 43
	s_cselect_b64 s[0:1], -1, 0
	v_writelane_b32 v254, s0, 44
	s_nop 1
	v_writelane_b32 v254, s1, 45
	v_writelane_b32 v254, s4, 46
	s_cmp_lg_u64 s[10:11], 0
	s_cselect_b64 s[0:1], -1, 0
	v_writelane_b32 v254, s5, 47
	v_writelane_b32 v254, s6, 48
	v_writelane_b32 v254, s7, 49
	v_writelane_b32 v254, s8, 50
	v_writelane_b32 v254, s9, 51
	v_writelane_b32 v254, s10, 52
	v_writelane_b32 v254, s11, 53
	v_writelane_b32 v254, s12, 54
	v_writelane_b32 v254, s13, 55
	v_writelane_b32 v254, s14, 56
	v_writelane_b32 v254, s15, 57
	v_writelane_b32 v254, s16, 58
	v_writelane_b32 v254, s17, 59
	v_writelane_b32 v254, s18, 60
	v_writelane_b32 v254, s19, 61
	v_writelane_b32 v254, s0, 62
	s_cmpk_lt_i32 s88, 0x200
	v_readlane_b32 s4, v253, 32
	v_writelane_b32 v254, s1, 63
	s_cselect_b64 s[0:1], -1, 0
	v_writelane_b32 v255, s0, 0
	s_cmpk_lt_i32 s88, 0x800
	v_readlane_b32 s10, v253, 38
	v_writelane_b32 v255, s1, 1
	s_cselect_b64 s[0:1], -1, 0
	v_readlane_b32 s11, v253, 39
	v_writelane_b32 v255, s0, 2
	s_cmp_lg_u64 s[10:11], 0
	v_readlane_b32 s5, v253, 33
	v_writelane_b32 v255, s1, 3
	s_cselect_b64 s[0:1], -1, 0
	v_writelane_b32 v255, s0, 4
	s_cmp_lg_u64 s[4:5], 0
	s_mov_b32 s10, s84
	v_writelane_b32 v255, s1, 5
	s_cselect_b64 s[0:1], -1, 0
	v_writelane_b32 v255, s0, 6
	s_cmpk_lt_i32 s88, 0xd80
	v_readlane_b32 s13, v253, 41
	v_writelane_b32 v255, s1, 7
	s_cselect_b64 s[0:1], -1, 0
	v_writelane_b32 v255, s0, 8
	s_cmpk_lt_i32 s88, 0x3ac4
	s_movk_i32 s13, 0x84
	v_writelane_b32 v255, s1, 9
	s_cselect_b64 s[0:1], -1, 0
	v_writelane_b32 v255, s0, 10
	v_readlane_b32 s6, v253, 34
	v_readlane_b32 s7, v253, 35
	v_writelane_b32 v255, s1, 11
	v_cmp_eq_u32_e64 s[0:1], 0, v0
	v_readlane_b32 s8, v253, 36
	v_readlane_b32 s9, v253, 37
	v_writelane_b32 v255, s0, 12
	v_readlane_b32 s12, v253, 40
	v_readlane_b32 s14, v253, 42
	v_writelane_b32 v255, s1, 13
	s_add_u32 s0, s22, 0x80
	v_writelane_b32 v255, s20, 14
	s_addc_u32 s1, s23, 0
	v_readlane_b32 s15, v253, 43
	v_writelane_b32 v255, s21, 15
	v_writelane_b32 v255, s22, 16
	v_writelane_b32 v255, s23, 17
	v_writelane_b32 v255, s0, 18
	v_readlane_b32 s16, v253, 44
	v_readlane_b32 s17, v253, 45
	v_writelane_b32 v255, s1, 19
	s_add_u32 s0, s80, 0x80
	v_writelane_b32 v255, s0, 20
	s_addc_u32 s0, s81, 0
	v_writelane_b32 v255, s0, 21
	v_writelane_b32 v255, s2, 22
	v_writelane_b32 v255, s84, 23
	s_mov_b32 s0, 0x5040100
	s_movk_i32 s1, 0x1580
	v_writelane_b32 v255, s85, 24
	v_writelane_b32 v255, s88, 25
	v_readlane_b32 s18, v253, 46
	v_readlane_b32 s19, v253, 47
	s_branch .LBB0_3

; template <bool NORM, bool DEEP, int MTW, int KSEG, class HOOK>
; DI void gemm_core_h(const bfu* __restrict__ A, int lda, const bfu* __restrict__ Bt, int ldb, int K, int m0, int n0,
;                     f32x16 (&acc)[MTW][2], char* smem, HOOK hook) {
;     ...
;   if (DEEP) {
;     for (int kt = 0; kt < nk; kt += 2) {
;       GEMM_STEP(ra0, rb0, kt, 2)
;       GEMM_STEP(ra1, rb1, kt + 1, 2)
;     }
;   } else {
;     for (int kt = 0; kt < nk; ++kt) {
;       GEMM_STEP(ra0, rb0, kt, 1)
;       if (KSEG > 0) { if (((kt + 1) % (KSEG > 0 ? KSEG : 1)) == 0) hook((kt + 1) / (KSEG > 0 ? KSEG : 1) - 1); }
;     }
.LBB0_96:
	s_waitcnt lgkmcnt(0)
	s_barrier
	s_waitcnt vmcnt(7)
	ds_write_b128 v183, v[148:151]
	s_waitcnt vmcnt(6)
	ds_write_b128 v183, v[144:147] offset:4608
	s_waitcnt vmcnt(5)
	ds_write_b128 v183, v[156:159] offset:9216
	s_waitcnt vmcnt(4)
	ds_write_b128 v183, v[152:155] offset:13824
	s_waitcnt vmcnt(3)
	ds_write_b128 v183, v[164:167] offset:18432
	s_waitcnt vmcnt(2)
	ds_write_b128 v183, v[160:163] offset:23040
	s_waitcnt vmcnt(1)
	ds_write_b128 v183, v[168:171] offset:27648
	s_waitcnt vmcnt(0)
	ds_write_b128 v183, v[172:175] offset:32256
	ds_write_b128 v183, v[140:143] offset:36864
	ds_write_b128 v183, v[136:139] offset:41472
	ds_write_b128 v183, v[128:131] offset:46080
	ds_write_b128 v183, v[132:135] offset:50688
	s_waitcnt lgkmcnt(0)
	s_barrier
	ds_read_b128 v[128:131], v179
	ds_read_b128 v[132:135], v182 offset:36864
	ds_read_b128 v[136:139], v182 offset:36896
	ds_read_b128 v[140:143], v179 offset:32
	ds_read_b128 v[144:147], v182 offset:41472
	ds_read_b128 v[148:151], v182 offset:41504
	s_waitcnt lgkmcnt(4)
	v_mfma_f32_32x32x16_bf16 v[112:127], v[128:131], v[132:135], v[112:127]
	s_waitcnt lgkmcnt(1)
	v_mfma_f32_32x32x16_bf16 v[96:111], v[128:131], v[144:147], v[96:111]
	ds_read_b128 v[128:131], v179 offset:4608
	ds_read_b128 v[152:155], v179 offset:4640
	s_waitcnt lgkmcnt(1)
	v_mfma_f32_32x32x16_bf16 v[80:95], v[128:131], v[132:135], v[80:95]
	v_mfma_f32_32x32x16_bf16 v[64:79], v[128:131], v[144:147], v[64:79]
	ds_read_b128 v[128:131], v179 offset:9216
	ds_read_b128 v[156:159], v179 offset:9248
	s_waitcnt lgkmcnt(1)
	v_mfma_f32_32x32x16_bf16 v[48:63], v[128:131], v[132:135], v[48:63]
	v_mfma_f32_32x32x16_bf16 v[32:47], v[128:131], v[144:147], v[32:47]
	ds_read_b128 v[128:131], v177
	ds_read_b128 v[160:163], v177 offset:32
	s_waitcnt lgkmcnt(1)
	v_mfma_f32_32x32x16_bf16 v[16:31], v[128:131], v[132:135], v[16:31]
	v_mfma_f32_32x32x16_bf16 v[0:15], v[128:131], v[144:147], v[0:15]
	v_mfma_f32_32x32x16_bf16 v[112:127], v[140:143], v[136:139], v[112:127]
	v_mfma_f32_32x32x16_bf16 v[96:111], v[140:143], v[148:151], v[96:111]
	v_mfma_f32_32x32x16_bf16 v[80:95], v[152:155], v[136:139], v[80:95]
	v_mfma_f32_32x32x16_bf16 v[64:79], v[152:155], v[148:151], v[64:79]
	v_mfma_f32_32x32x16_bf16 v[48:63], v[156:159], v[136:139], v[48:63]
	s_waitcnt lgkmcnt(0)
	v_mfma_f32_32x32x16_bf16 v[16:31], v[160:163], v[136:139], v[16:31]
	ds_read_b128 v[128:131], v179 offset:64
	ds_read_b128 v[132:135], v182 offset:36928
	ds_read_b128 v[184:187], v182 offset:36960
	ds_read_b128 v[136:139], v179 offset:96
	ds_read_b128 v[140:143], v182 offset:41536
	ds_read_b128 v[190:193], v182 offset:41568
	v_mfma_f32_32x32x16_bf16 v[32:47], v[156:159], v[148:151], v[32:47]
	v_mfma_f32_32x32x16_bf16 v[0:15], v[160:163], v[148:151], v[0:15]
	s_waitcnt lgkmcnt(4)
	v_mfma_f32_32x32x16_bf16 v[112:127], v[128:131], v[132:135], v[112:127]
	s_waitcnt lgkmcnt(1)
	v_mfma_f32_32x32x16_bf16 v[96:111], v[128:131], v[140:143], v[96:111]
	ds_read_b128 v[128:131], v179 offset:4672
	ds_read_b128 v[160:163], v179 offset:4704
	s_waitcnt lgkmcnt(1)
	v_mfma_f32_32x32x16_bf16 v[80:95], v[128:131], v[132:135], v[80:95]
	v_mfma_f32_32x32x16_bf16 v[64:79], v[128:131], v[140:143], v[64:79]
	ds_read_b128 v[128:131], v179 offset:9280
	ds_read_b128 v[194:197], v179 offset:9312
	s_waitcnt lgkmcnt(1)
	v_mfma_f32_32x32x16_bf16 v[48:63], v[128:131], v[132:135], v[48:63]
	v_mfma_f32_32x32x16_bf16 v[32:47], v[128:131], v[140:143], v[32:47]
	ds_read_b128 v[128:131], v177 offset:64
	ds_read_b128 v[198:201], v177 offset:96
	s_waitcnt lgkmcnt(1)
	v_mfma_f32_32x32x16_bf16 v[16:31], v[128:131], v[132:135], v[16:31]
	v_add_u32_e32 v132, s5, v176
	v_add_u32_e32 v188, 64, v132
	v_add_u32_e32 v133, s5, v178
	s_add_i32 s5, s5, 64
	s_cmpk_lg_i32 s5, 0xfc0
	v_mfma_f32_32x32x16_bf16 v[0:15], v[128:131], v[140:143], v[0:15]
	v_lshl_add_u64 v[128:129], v[188:189], 1, s[72:73]
	v_add_u32_e32 v188, 0x20040, v132
	v_lshl_add_u64 v[130:131], v[188:189], 1, s[72:73]
	v_add_u32_e32 v188, 0x40040, v132
	global_load_dwordx4 v[148:151], v[128:129], off
	global_load_dwordx4 v[144:147], v[130:131], off
	v_lshl_add_u64 v[128:129], v[188:189], 1, s[72:73]
	v_add_u32_e32 v188, 0x60040, v132
	v_lshl_add_u64 v[130:131], v[188:189], 1, s[72:73]
	v_add_u32_e32 v188, 0x80040, v132
	global_load_dwordx4 v[156:159], v[128:129], off
	global_load_dwordx4 v[152:155], v[130:131], off
	v_lshl_add_u64 v[128:129], v[188:189], 1, s[72:73]
	v_add_u32_e32 v188, 0xa0040, v132
	v_lshl_add_u64 v[130:131], v[188:189], 1, s[72:73]
	v_add_u32_e32 v188, 0xc0040, v132
	v_mfma_f32_32x32x16_bf16 v[80:95], v[160:163], v[184:187], v[80:95]
	v_mfma_f32_32x32x16_bf16 v[64:79], v[160:163], v[190:193], v[64:79]
	global_load_dwordx4 v[164:167], v[128:129], off
	global_load_dwordx4 v[160:163], v[130:131], off
	v_lshl_add_u64 v[128:129], v[188:189], 1, s[72:73]
	v_add_u32_e32 v188, 0xe0040, v132
	v_lshl_add_u64 v[130:131], v[188:189], 1, s[72:73]
	v_add_u32_e32 v188, 64, v133
	global_load_dwordx4 v[168:171], v[128:129], off
	global_load_dwordx4 v[172:175], v[130:131], off
	v_lshl_add_u64 v[128:129], v[188:189], 1, s[26:27]
	v_add_u32_e32 v188, 0x20040, v133
	v_lshl_add_u64 v[130:131], v[188:189], 1, s[26:27]
	v_add_u32_e32 v188, 0x40040, v133
	v_mfma_f32_32x32x16_bf16 v[112:127], v[136:139], v[184:187], v[112:127]
	v_mfma_f32_32x32x16_bf16 v[96:111], v[136:139], v[190:193], v[96:111]
	global_load_dwordx4 v[140:143], v[128:129], off
	global_load_dwordx4 v[136:139], v[130:131], off
	v_lshl_add_u64 v[128:129], v[188:189], 1, s[26:27]
	v_add_u32_e32 v188, 0x60040, v133
	v_lshl_add_u64 v[132:133], v[188:189], 1, s[26:27]
	global_load_dwordx4 v[128:131], v[128:129], off
	s_nop 0
	global_load_dwordx4 v[132:135], v[132:133], off
	v_mfma_f32_32x32x16_bf16 v[48:63], v[194:197], v[184:187], v[48:63]
	v_mfma_f32_32x32x16_bf16 v[32:47], v[194:197], v[190:193], v[32:47]
	s_waitcnt lgkmcnt(0)
	v_mfma_f32_32x32x16_bf16 v[16:31], v[198:201], v[184:187], v[16:31]
	v_mfma_f32_32x32x16_bf16 v[0:15], v[198:201], v[190:193], v[0:15]
	s_cbranch_scc1 .LBB0_96
	s_waitcnt lgkmcnt(0)
	s_barrier
	s_waitcnt vmcnt(11)
	ds_write_b128 v183, v[148:151]
	s_waitcnt vmcnt(10)
	ds_write_b128 v183, v[144:147] offset:4608
	s_waitcnt vmcnt(9)
	ds_write_b128 v183, v[156:159] offset:9216
	s_waitcnt vmcnt(8)
	ds_write_b128 v183, v[152:155] offset:13824
	s_waitcnt vmcnt(7)
	ds_write_b128 v183, v[164:167] offset:18432
	s_waitcnt vmcnt(6)
	ds_write_b128 v183, v[160:163] offset:23040
	s_waitcnt vmcnt(5)
	ds_write_b128 v183, v[168:171] offset:27648
	s_waitcnt vmcnt(4)
	ds_write_b128 v183, v[172:175] offset:32256
	s_waitcnt vmcnt(3)
	ds_write_b128 v183, v[140:143] offset:36864
	s_waitcnt vmcnt(2)
	ds_write_b128 v183, v[136:139] offset:41472
	s_waitcnt vmcnt(1)
	ds_write_b128 v183, v[128:131] offset:46080
	s_waitcnt vmcnt(0)
	ds_write_b128 v183, v[132:135] offset:50688
	s_waitcnt lgkmcnt(0)
	s_barrier
	ds_read_b128 v[128:131], v182 offset:41472
	ds_read_b128 v[132:135], v182 offset:36864
	ds_read_b128 v[136:139], v182 offset:36896
	ds_read_b128 v[140:143], v179
	ds_read_b128 v[144:147], v179 offset:32
	s_waitcnt lgkmcnt(1)
	v_mfma_f32_32x32x16_bf16 v[112:127], v[140:143], v[132:135], v[112:127]
	v_readlane_b32 s16, v253, 32
	v_readlane_b32 s28, v253, 44
	v_readlane_b32 s29, v253, 45
	v_readlane_b32 s17, v253, 33
	v_readlane_b32 s18, v253, 34
	v_readlane_b32 s19, v253, 35
	v_readlane_b32 s20, v253, 36
	v_mfma_f32_32x32x16_bf16 v[96:111], v[140:143], v[128:131], v[96:111]
	ds_read_b128 v[140:143], v179 offset:4608
	v_readlane_b32 s21, v253, 37
	v_readlane_b32 s22, v253, 38
	v_readlane_b32 s23, v253, 39
	v_readlane_b32 s24, v253, 40
	v_readlane_b32 s25, v253, 41
	v_readlane_b32 s26, v253, 42
	s_waitcnt lgkmcnt(0)
	v_mfma_f32_32x32x16_bf16 v[80:95], v[140:143], v[132:135], v[80:95]
	v_readlane_b32 s27, v253, 43
	v_readlane_b32 s30, v253, 46
	v_readlane_b32 s31, v253, 47
	v_mfma_f32_32x32x16_bf16 v[64:79], v[140:143], v[128:131], v[64:79]
	ds_read_b128 v[140:143], v179 offset:9216
	s_waitcnt lgkmcnt(0)
	v_mfma_f32_32x32x16_bf16 v[48:63], v[140:143], v[132:135], v[48:63]
	v_mfma_f32_32x32x16_bf16 v[32:47], v[140:143], v[128:131], v[32:47]
	ds_read_b128 v[140:143], v177
	ds_read_b128 v[148:151], v177 offset:32
	s_waitcnt lgkmcnt(1)
	v_mfma_f32_32x32x16_bf16 v[16:31], v[140:143], v[132:135], v[16:31]
	ds_read_b128 v[132:135], v179 offset:4640
	v_mfma_f32_32x32x16_bf16 v[0:15], v[140:143], v[128:131], v[0:15]
	ds_read_b128 v[128:131], v182 offset:41504
	s_waitcnt lgkmcnt(1)
	v_mfma_f32_32x32x16_bf16 v[80:95], v[132:135], v[136:139], v[80:95]
	s_waitcnt lgkmcnt(0)
	v_mfma_f32_32x32x16_bf16 v[64:79], v[132:135], v[128:131], v[64:79]
	ds_read_b128 v[132:135], v179 offset:9248
	v_mfma_f32_32x32x16_bf16 v[112:127], v[144:147], v[136:139], v[112:127]
	v_mfma_f32_32x32x16_bf16 v[96:111], v[144:147], v[128:131], v[96:111]
	s_waitcnt lgkmcnt(0)
	v_mfma_f32_32x32x16_bf16 v[48:63], v[132:135], v[136:139], v[48:63]
	v_mfma_f32_32x32x16_bf16 v[32:47], v[132:135], v[128:131], v[32:47]
	v_mfma_f32_32x32x16_bf16 v[16:31], v[148:151], v[136:139], v[16:31]
	v_mfma_f32_32x32x16_bf16 v[0:15], v[148:151], v[128:131], v[0:15]
	ds_read_b128 v[128:131], v182 offset:36928
	ds_read_b128 v[132:135], v182 offset:41536
	ds_read_b128 v[136:139], v179 offset:64
	s_waitcnt lgkmcnt(0)
	v_mfma_f32_32x32x16_bf16 v[112:127], v[136:139], v[128:131], v[112:127]
	v_mfma_f32_32x32x16_bf16 v[96:111], v[136:139], v[132:135], v[96:111]
	ds_read_b128 v[136:139], v179 offset:4672
	s_waitcnt lgkmcnt(0)
	v_mfma_f32_32x32x16_bf16 v[80:95], v[136:139], v[128:131], v[80:95]
	v_mfma_f32_32x32x16_bf16 v[64:79], v[136:139], v[132:135], v[64:79]
	ds_read_b128 v[136:139], v179 offset:9280
	s_waitcnt lgkmcnt(0)
	v_mfma_f32_32x32x16_bf16 v[48:63], v[136:139], v[128:131], v[48:63]
	v_mfma_f32_32x32x16_bf16 v[32:47], v[136:139], v[132:135], v[32:47]
	ds_read_b128 v[136:139], v177 offset:64
	s_waitcnt lgkmcnt(0)
	v_mfma_f32_32x32x16_bf16 v[16:31], v[136:139], v[128:131], v[16:31]
	v_mfma_f32_32x32x16_bf16 v[0:15], v[136:139], v[132:135], v[0:15]
	ds_read_b128 v[128:131], v182 offset:36960
	ds_read_b128 v[132:135], v182 offset:41568
	ds_read_b128 v[136:139], v179 offset:96
	s_waitcnt lgkmcnt(0)
	v_mfma_f32_32x32x16_bf16 v[112:127], v[136:139], v[128:131], v[112:127]
	v_mfma_f32_32x32x16_bf16 v[96:111], v[136:139], v[132:135], v[96:111]
	ds_read_b128 v[136:139], v179 offset:4704
	s_waitcnt lgkmcnt(0)
	v_mfma_f32_32x32x16_bf16 v[80:95], v[136:139], v[128:131], v[80:95]
	v_mfma_f32_32x32x16_bf16 v[64:79], v[136:139], v[132:135], v[64:79]
	ds_read_b128 v[136:139], v179 offset:9312
	s_waitcnt lgkmcnt(0)
	v_mfma_f32_32x32x16_bf16 v[48:63], v[136:139], v[128:131], v[48:63]
	v_mfma_f32_32x32x16_bf16 v[32:47], v[136:139], v[132:135], v[32:47]
	ds_read_b128 v[136:139], v177 offset:96
	s_waitcnt lgkmcnt(0)
	s_barrier
; #define ZERO_ACCM(a, MT) _Pragma("unroll") for (int _m = 0; _m < MT; ++_m) _Pragma("unroll") for (int _n = 0; _n < 2; ++_n) _Pragma("unroll") for (int _i = 0; _i < 16; ++_i) a[_m][_n][_i] = 0.f;
; DI void phase_resid(const Params& p, const bfu* A, int lda, const bfu* Bt, int K, char* smem) {
;   GEMM_IDS
;   for (int id = blockIdx.x; id < 64 * 8; id += gridDim.x) {
;     int tm, tn; map_tile(id, 8, tm, tn);
;     const int m0 = tm * 256, n0 = tn * 128;
;     f32x16 acc[4][2]; ZERO_ACCM(acc, 4)
;     gemm_core<false, false, 4>(A, lda, Bt, K, K, m0, n0, acc, smem);
;     EPI_BEGINM(acc, 4)
;       float* xp = p.out + (size_t)row * 1024 + col;
;       float nv = *xp + v; *xp = nv; p.xb[(size_t)row * 1024 + col] = f2bf(nv);
;     EPI_END
;   }
	v_mfma_f32_32x32x16_bf16 v[16:31], v[136:139], v[128:131], v[16:31]
	v_mfma_f32_32x32x16_bf16 v[0:15], v[136:139], v[132:135], v[0:15]
	v_add_u32_e32 v176, s3, v180
	v_or_b32_e32 v177, s4, v181
	v_lshlrev_b32_e32 v176, 12, v176
	v_lshl_add_u32 v176, v177, 2, v176
	v_lshrrev_b32_e32 v177, 1, v176
	v_readlane_b32 s4, v254, 38
	v_readlane_b32 s5, v254, 39
	global_load_dword v128, v176, s[28:29]
	global_load_dword v129, v176, s[28:29] offset:128
	v_add_u32_e32 v178, 0x1000, v176
	global_load_dword v130, v178, s[28:29]
	global_load_dword v131, v178, s[28:29] offset:128
	v_add_u32_e32 v178, 0x2000, v176
	global_load_dword v132, v178, s[28:29]
	global_load_dword v133, v178, s[28:29] offset:128
	v_add_u32_e32 v178, 0x3000, v176
	global_load_dword v134, v178, s[28:29]
	global_load_dword v135, v178, s[28:29] offset:128
	v_add_u32_e32 v178, 0x8000, v176
	global_load_dword v136, v178, s[28:29]
	global_load_dword v137, v178, s[28:29] offset:128
	v_add_u32_e32 v178, 0x9000, v176
	global_load_dword v138, v178, s[28:29]
	global_load_dword v139, v178, s[28:29] offset:128
	v_add_u32_e32 v178, 0xa000, v176
	global_load_dword v140, v178, s[28:29]
	global_load_dword v141, v178, s[28:29] offset:128
	v_add_u32_e32 v178, 0xb000, v176
	global_load_dword v142, v178, s[28:29]
	global_load_dword v143, v178, s[28:29] offset:128
	v_add_u32_e32 v178, 0x10000, v176
	global_load_dword v144, v178, s[28:29]
	global_load_dword v145, v178, s[28:29] offset:128
	v_add_u32_e32 v178, 0x11000, v176
	global_load_dword v146, v178, s[28:29]
	global_load_dword v147, v178, s[28:29] offset:128
	v_add_u32_e32 v178, 0x12000, v176
	global_load_dword v148, v178, s[28:29]
	global_load_dword v149, v178, s[28:29] offset:128
	v_add_u32_e32 v178, 0x13000, v176
	global_load_dword v150, v178, s[28:29]
	global_load_dword v151, v178, s[28:29] offset:128
	v_add_u32_e32 v178, 0x18000, v176
	global_load_dword v152, v178, s[28:29]
	global_load_dword v153, v178, s[28:29] offset:128
	v_add_u32_e32 v178, 0x19000, v176
	global_load_dword v154, v178, s[28:29]
	global_load_dword v155, v178, s[28:29] offset:128
	v_add_u32_e32 v178, 0x1a000, v176
	global_load_dword v156, v178, s[28:29]
	global_load_dword v157, v178, s[28:29] offset:128
	v_add_u32_e32 v178, 0x1b000, v176
	global_load_dword v158, v178, s[28:29]
	global_load_dword v159, v178, s[28:29] offset:128
	v_add_u32_e32 v178, 0x20000, v176
	global_load_dword v160, v178, s[28:29]
	global_load_dword v161, v178, s[28:29] offset:128
	v_add_u32_e32 v178, 0x21000, v176
	global_load_dword v162, v178, s[28:29]
	global_load_dword v163, v178, s[28:29] offset:128
	v_add_u32_e32 v178, 0x22000, v176
	global_load_dword v164, v178, s[28:29]
	global_load_dword v165, v178, s[28:29] offset:128
	v_add_u32_e32 v178, 0x23000, v176
	global_load_dword v166, v178, s[28:29]
	global_load_dword v167, v178, s[28:29] offset:128
	v_add_u32_e32 v178, 0x28000, v176
	global_load_dword v168, v178, s[28:29]
	global_load_dword v169, v178, s[28:29] offset:128
	v_add_u32_e32 v178, 0x29000, v176
	global_load_dword v170, v178, s[28:29]
	global_load_dword v171, v178, s[28:29] offset:128
	v_add_u32_e32 v178, 0x2a000, v176
	global_load_dword v172, v178, s[28:29]
	global_load_dword v173, v178, s[28:29] offset:128
	v_add_u32_e32 v178, 0x2b000, v176
	global_load_dword v174, v178, s[28:29]
	global_load_dword v175, v178, s[28:29] offset:128
	v_add_u32_e32 v178, 0x30000, v176
	global_load_dword v184, v178, s[28:29]
	global_load_dword v185, v178, s[28:29] offset:128
	v_add_u32_e32 v178, 0x31000, v176
	global_load_dword v186, v178, s[28:29]
	global_load_dword v187, v178, s[28:29] offset:128
	v_add_u32_e32 v178, 0x32000, v176
	global_load_dword v190, v178, s[28:29]
	global_load_dword v191, v178, s[28:29] offset:128
	v_add_u32_e32 v178, 0x33000, v176
	global_load_dword v192, v178, s[28:29]
	global_load_dword v193, v178, s[28:29] offset:128
	v_add_u32_e32 v178, 0x38000, v176
	global_load_dword v194, v178, s[28:29]
	global_load_dword v195, v178, s[28:29] offset:128
	v_add_u32_e32 v178, 0x39000, v176
	global_load_dword v196, v178, s[28:29]
	global_load_dword v197, v178, s[28:29] offset:128
	v_add_u32_e32 v178, 0x3a000, v176
	global_load_dword v198, v178, s[28:29]
	global_load_dword v199, v178, s[28:29] offset:128
	v_add_u32_e32 v178, 0x3b000, v176
	global_load_dword v200, v178, s[28:29]
	global_load_dword v201, v178, s[28:29] offset:128
	s_waitcnt vmcnt(32)
; DI void phase_resid(const Params& p, const bfu* A, int lda, const bfu* Bt, int K, char* smem) {
;     ...
;     EPI_BEGINM(acc, 4)
;       float* xp = p.out + (size_t)row * 1024 + col;
;       float nv = *xp + v; *xp = nv; p.xb[(size_t)row * 1024 + col] = f2bf(nv);
;     EPI_END
	v_add_f32_e32 v112, v112, v128
	global_store_dword v176, v112, s[28:29]
	v_cvt_pk_bf16_f32 v128, v112, v112
	global_store_short v177, v128, s[36:37]
	v_add_f32_e32 v96, v96, v129
	global_store_dword v176, v96, s[28:29] offset:128
	v_cvt_pk_bf16_f32 v129, v96, v96
	global_store_short v177, v129, s[36:37] offset:64
	v_add_u32_e32 v178, 0x1000, v176
	v_add_u32_e32 v179, 0x800, v177
	v_add_f32_e32 v113, v113, v130
	global_store_dword v178, v113, s[28:29]
	v_cvt_pk_bf16_f32 v130, v113, v113
	global_store_short v179, v130, s[36:37]
	v_add_f32_e32 v97, v97, v131
	global_store_dword v178, v97, s[28:29] offset:128
	v_cvt_pk_bf16_f32 v131, v97, v97
	global_store_short v179, v131, s[36:37] offset:64
	v_add_u32_e32 v178, 0x2000, v176
	v_add_u32_e32 v179, 0x1000, v177
	v_add_f32_e32 v114, v114, v132
	global_store_dword v178, v114, s[28:29]
	v_cvt_pk_bf16_f32 v132, v114, v114
	global_store_short v179, v132, s[36:37]
	v_add_f32_e32 v98, v98, v133
	global_store_dword v178, v98, s[28:29] offset:128
	v_cvt_pk_bf16_f32 v133, v98, v98
	global_store_short v179, v133, s[36:37] offset:64
	v_add_u32_e32 v178, 0x3000, v176
	v_add_u32_e32 v179, 0x1800, v177
	v_add_f32_e32 v115, v115, v134
	global_store_dword v178, v115, s[28:29]
	v_cvt_pk_bf16_f32 v134, v115, v115
	global_store_short v179, v134, s[36:37]
	v_add_f32_e32 v99, v99, v135
	global_store_dword v178, v99, s[28:29] offset:128
	v_cvt_pk_bf16_f32 v135, v99, v99
	global_store_short v179, v135, s[36:37] offset:64
	v_add_u32_e32 v178, 0x8000, v176
	v_add_u32_e32 v179, 0x4000, v177
	v_add_f32_e32 v116, v116, v136
	global_store_dword v178, v116, s[28:29]
	v_cvt_pk_bf16_f32 v136, v116, v116
	global_store_short v179, v136, s[36:37]
	v_add_f32_e32 v100, v100, v137
	global_store_dword v178, v100, s[28:29] offset:128
	v_cvt_pk_bf16_f32 v137, v100, v100
	global_store_short v179, v137, s[36:37] offset:64
	v_add_u32_e32 v178, 0x9000, v176
	v_add_u32_e32 v179, 0x4800, v177
	v_add_f32_e32 v117, v117, v138
	global_store_dword v178, v117, s[28:29]
	v_cvt_pk_bf16_f32 v138, v117, v117
	global_store_short v179, v138, s[36:37]
	v_add_f32_e32 v101, v101, v139
	global_store_dword v178, v101, s[28:29] offset:128
	v_cvt_pk_bf16_f32 v139, v101, v101
	global_store_short v179, v139, s[36:37] offset:64
	v_add_u32_e32 v178, 0xa000, v176
	v_add_u32_e32 v179, 0x5000, v177
	v_add_f32_e32 v118, v118, v140
	global_store_dword v178, v118, s[28:29]
	v_cvt_pk_bf16_f32 v140, v118, v118
	global_store_short v179, v140, s[36:37]
	v_add_f32_e32 v102, v102, v141
	global_store_dword v178, v102, s[28:29] offset:128
	v_cvt_pk_bf16_f32 v141, v102, v102
	global_store_short v179, v141, s[36:37] offset:64
	v_add_u32_e32 v178, 0xb000, v176
	v_add_u32_e32 v179, 0x5800, v177
	v_add_f32_e32 v119, v119, v142
	global_store_dword v178, v119, s[28:29]
	v_cvt_pk_bf16_f32 v142, v119, v119
	global_store_short v179, v142, s[36:37]
	v_add_f32_e32 v103, v103, v143
	global_store_dword v178, v103, s[28:29] offset:128
	v_cvt_pk_bf16_f32 v143, v103, v103
	global_store_short v179, v143, s[36:37] offset:64
	v_add_u32_e32 v178, 0x10000, v176
	v_add_u32_e32 v179, 0x8000, v177
	v_add_f32_e32 v120, v120, v144
	global_store_dword v178, v120, s[28:29]
	v_cvt_pk_bf16_f32 v144, v120, v120
	global_store_short v179, v144, s[36:37]
	v_add_f32_e32 v104, v104, v145
	global_store_dword v178, v104, s[28:29] offset:128
	v_cvt_pk_bf16_f32 v145, v104, v104
	global_store_short v179, v145, s[36:37] offset:64
	v_add_u32_e32 v178, 0x11000, v176
	v_add_u32_e32 v179, 0x8800, v177
	v_add_f32_e32 v121, v121, v146
	global_store_dword v178, v121, s[28:29]
	v_cvt_pk_bf16_f32 v146, v121, v121
	global_store_short v179, v146, s[36:37]
	v_add_f32_e32 v105, v105, v147
	global_store_dword v178, v105, s[28:29] offset:128
	v_cvt_pk_bf16_f32 v147, v105, v105
	global_store_short v179, v147, s[36:37] offset:64
	v_add_u32_e32 v178, 0x12000, v176
	v_add_u32_e32 v179, 0x9000, v177
	v_add_f32_e32 v122, v122, v148
	global_store_dword v178, v122, s[28:29]
	v_cvt_pk_bf16_f32 v148, v122, v122
	global_store_short v179, v148, s[36:37]
	v_add_f32_e32 v106, v106, v149
	global_store_dword v178, v106, s[28:29] offset:128
	v_cvt_pk_bf16_f32 v149, v106, v106
	global_store_short v179, v149, s[36:37] offset:64
	v_add_u32_e32 v178, 0x13000, v176
	v_add_u32_e32 v179, 0x9800, v177
	v_add_f32_e32 v123, v123, v150
	global_store_dword v178, v123, s[28:29]
	v_cvt_pk_bf16_f32 v150, v123, v123
	global_store_short v179, v150, s[36:37]
	v_add_f32_e32 v107, v107, v151
	global_store_dword v178, v107, s[28:29] offset:128
	v_cvt_pk_bf16_f32 v151, v107, v107
	global_store_short v179, v151, s[36:37] offset:64
	v_add_u32_e32 v178, 0x18000, v176
	v_add_u32_e32 v179, 0xc000, v177
	v_add_f32_e32 v124, v124, v152
	global_store_dword v178, v124, s[28:29]
	v_cvt_pk_bf16_f32 v152, v124, v124
	global_store_short v179, v152, s[36:37]
	v_add_f32_e32 v108, v108, v153
	global_store_dword v178, v108, s[28:29] offset:128
	v_cvt_pk_bf16_f32 v153, v108, v108
	global_store_short v179, v153, s[36:37] offset:64
	v_add_u32_e32 v178, 0x19000, v176
	v_add_u32_e32 v179, 0xc800, v177
	v_add_f32_e32 v125, v125, v154
	global_store_dword v178, v125, s[28:29]
	v_cvt_pk_bf16_f32 v154, v125, v125
	global_store_short v179, v154, s[36:37]
	v_add_f32_e32 v109, v109, v155
	global_store_dword v178, v109, s[28:29] offset:128
	v_cvt_pk_bf16_f32 v155, v109, v109
	global_store_short v179, v155, s[36:37] offset:64
	v_add_u32_e32 v178, 0x1a000, v176
	v_add_u32_e32 v179, 0xd000, v177
	v_add_f32_e32 v126, v126, v156
	global_store_dword v178, v126, s[28:29]
	v_cvt_pk_bf16_f32 v156, v126, v126
	global_store_short v179, v156, s[36:37]
	v_add_f32_e32 v110, v110, v157
; DI void phase_resid(const Params& p, const bfu* A, int lda, const bfu* Bt, int K, char* smem) {
;     ...
;     EPI_BEGINM(acc, 4)
;       float* xp = p.out + (size_t)row * 1024 + col;
;       float nv = *xp + v; *xp = nv; p.xb[(size_t)row * 1024 + col] = f2bf(nv);
;     EPI_END
	global_store_dword v178, v110, s[28:29] offset:128
	v_cvt_pk_bf16_f32 v157, v110, v110
	global_store_short v179, v157, s[36:37] offset:64
	v_add_u32_e32 v178, 0x1b000, v176
	v_add_u32_e32 v179, 0xd800, v177
	v_add_f32_e32 v127, v127, v158
	global_store_dword v178, v127, s[28:29]
	v_cvt_pk_bf16_f32 v158, v127, v127
	global_store_short v179, v158, s[36:37]
	v_add_f32_e32 v111, v111, v159
	global_store_dword v178, v111, s[28:29] offset:128
	v_cvt_pk_bf16_f32 v159, v111, v111
	global_store_short v179, v159, s[36:37] offset:64
	v_add_u32_e32 v178, 0x40000, v176
	global_load_dword v128, v178, s[28:29]
	global_load_dword v129, v178, s[28:29] offset:128
	v_add_u32_e32 v178, 0x41000, v176
	global_load_dword v130, v178, s[28:29]
	global_load_dword v131, v178, s[28:29] offset:128
	v_add_u32_e32 v178, 0x42000, v176
	global_load_dword v132, v178, s[28:29]
	global_load_dword v133, v178, s[28:29] offset:128
	v_add_u32_e32 v178, 0x43000, v176
	global_load_dword v134, v178, s[28:29]
	global_load_dword v135, v178, s[28:29] offset:128
	v_add_u32_e32 v178, 0x48000, v176
	global_load_dword v136, v178, s[28:29]
	global_load_dword v137, v178, s[28:29] offset:128
	v_add_u32_e32 v178, 0x49000, v176
	global_load_dword v138, v178, s[28:29]
	global_load_dword v139, v178, s[28:29] offset:128
	v_add_u32_e32 v178, 0x4a000, v176
	global_load_dword v140, v178, s[28:29]
	global_load_dword v141, v178, s[28:29] offset:128
	v_add_u32_e32 v178, 0x4b000, v176
	global_load_dword v142, v178, s[28:29]
	global_load_dword v143, v178, s[28:29] offset:128
	v_add_u32_e32 v178, 0x50000, v176
	global_load_dword v144, v178, s[28:29]
	global_load_dword v145, v178, s[28:29] offset:128
	v_add_u32_e32 v178, 0x51000, v176
	global_load_dword v146, v178, s[28:29]
	global_load_dword v147, v178, s[28:29] offset:128
	v_add_u32_e32 v178, 0x52000, v176
	global_load_dword v148, v178, s[28:29]
	global_load_dword v149, v178, s[28:29] offset:128
	v_add_u32_e32 v178, 0x53000, v176
	global_load_dword v150, v178, s[28:29]
	global_load_dword v151, v178, s[28:29] offset:128
	v_add_u32_e32 v178, 0x58000, v176
	global_load_dword v152, v178, s[28:29]
	global_load_dword v153, v178, s[28:29] offset:128
	v_add_u32_e32 v178, 0x59000, v176
	global_load_dword v154, v178, s[28:29]
	global_load_dword v155, v178, s[28:29] offset:128
	v_add_u32_e32 v178, 0x5a000, v176
	global_load_dword v156, v178, s[28:29]
	global_load_dword v157, v178, s[28:29] offset:128
	v_add_u32_e32 v178, 0x5b000, v176
	global_load_dword v158, v178, s[28:29]
	global_load_dword v159, v178, s[28:29] offset:128
	s_waitcnt vmcnt(63)
	v_add_u32_e32 v178, 0x20000, v176
	v_add_u32_e32 v179, 0x10000, v177
	v_add_f32_e32 v80, v80, v160
	global_store_dword v178, v80, s[28:29]
	v_cvt_pk_bf16_f32 v160, v80, v80
	global_store_short v179, v160, s[36:37]
	v_add_f32_e32 v64, v64, v161
	global_store_dword v178, v64, s[28:29] offset:128
	v_cvt_pk_bf16_f32 v161, v64, v64
	global_store_short v179, v161, s[36:37] offset:64
	v_add_u32_e32 v178, 0x21000, v176
	v_add_u32_e32 v179, 0x10800, v177
	v_add_f32_e32 v81, v81, v162
	global_store_dword v178, v81, s[28:29]
	v_cvt_pk_bf16_f32 v162, v81, v81
	global_store_short v179, v162, s[36:37]
	v_add_f32_e32 v65, v65, v163
	global_store_dword v178, v65, s[28:29] offset:128
	v_cvt_pk_bf16_f32 v163, v65, v65
	global_store_short v179, v163, s[36:37] offset:64
	v_add_u32_e32 v178, 0x22000, v176
	v_add_u32_e32 v179, 0x11000, v177
	v_add_f32_e32 v82, v82, v164
	global_store_dword v178, v82, s[28:29]
	v_cvt_pk_bf16_f32 v164, v82, v82
	global_store_short v179, v164, s[36:37]
	v_add_f32_e32 v66, v66, v165
	global_store_dword v178, v66, s[28:29] offset:128
	v_cvt_pk_bf16_f32 v165, v66, v66
	global_store_short v179, v165, s[36:37] offset:64
	v_add_u32_e32 v178, 0x23000, v176
	v_add_u32_e32 v179, 0x11800, v177
	v_add_f32_e32 v83, v83, v166
	global_store_dword v178, v83, s[28:29]
	v_cvt_pk_bf16_f32 v166, v83, v83
	global_store_short v179, v166, s[36:37]
	v_add_f32_e32 v67, v67, v167
	global_store_dword v178, v67, s[28:29] offset:128
	v_cvt_pk_bf16_f32 v167, v67, v67
	global_store_short v179, v167, s[36:37] offset:64
	v_add_u32_e32 v178, 0x28000, v176
	v_add_u32_e32 v179, 0x14000, v177
	v_add_f32_e32 v84, v84, v168
	global_store_dword v178, v84, s[28:29]
	v_cvt_pk_bf16_f32 v168, v84, v84
	global_store_short v179, v168, s[36:37]
	v_add_f32_e32 v68, v68, v169
	global_store_dword v178, v68, s[28:29] offset:128
	v_cvt_pk_bf16_f32 v169, v68, v68
	global_store_short v179, v169, s[36:37] offset:64
	v_add_u32_e32 v178, 0x29000, v176
	v_add_u32_e32 v179, 0x14800, v177
	v_add_f32_e32 v85, v85, v170
	global_store_dword v178, v85, s[28:29]
	v_cvt_pk_bf16_f32 v170, v85, v85
	global_store_short v179, v170, s[36:37]
	v_add_f32_e32 v69, v69, v171
	global_store_dword v178, v69, s[28:29] offset:128
	v_cvt_pk_bf16_f32 v171, v69, v69
	global_store_short v179, v171, s[36:37] offset:64
	v_add_u32_e32 v178, 0x2a000, v176
	v_add_u32_e32 v179, 0x15000, v177
	v_add_f32_e32 v86, v86, v172
	global_store_dword v178, v86, s[28:29]
	v_cvt_pk_bf16_f32 v172, v86, v86
	global_store_short v179, v172, s[36:37]
	v_add_f32_e32 v70, v70, v173
	global_store_dword v178, v70, s[28:29] offset:128
	v_cvt_pk_bf16_f32 v173, v70, v70
	global_store_short v179, v173, s[36:37] offset:64
	v_add_u32_e32 v178, 0x2b000, v176
	v_add_u32_e32 v179, 0x15800, v177
	v_add_f32_e32 v87, v87, v174
	global_store_dword v178, v87, s[28:29]
	v_cvt_pk_bf16_f32 v174, v87, v87
	global_store_short v179, v174, s[36:37]
	v_add_f32_e32 v71, v71, v175
	global_store_dword v178, v71, s[28:29] offset:128
	v_cvt_pk_bf16_f32 v175, v71, v71
	global_store_short v179, v175, s[36:37] offset:64
	v_add_u32_e32 v178, 0x30000, v176
; DI void phase_resid(const Params& p, const bfu* A, int lda, const bfu* Bt, int K, char* smem) {
;     ...
;     EPI_BEGINM(acc, 4)
;       float* xp = p.out + (size_t)row * 1024 + col;
;       float nv = *xp + v; *xp = nv; p.xb[(size_t)row * 1024 + col] = f2bf(nv);
;     EPI_END
	v_add_u32_e32 v179, 0x18000, v177
	v_add_f32_e32 v88, v88, v184
	global_store_dword v178, v88, s[28:29]
	v_cvt_pk_bf16_f32 v184, v88, v88
	global_store_short v179, v184, s[36:37]
	v_add_f32_e32 v72, v72, v185
	global_store_dword v178, v72, s[28:29] offset:128
	v_cvt_pk_bf16_f32 v185, v72, v72
	global_store_short v179, v185, s[36:37] offset:64
	v_add_u32_e32 v178, 0x31000, v176
	v_add_u32_e32 v179, 0x18800, v177
	v_add_f32_e32 v89, v89, v186
	global_store_dword v178, v89, s[28:29]
	v_cvt_pk_bf16_f32 v186, v89, v89
	global_store_short v179, v186, s[36:37]
	v_add_f32_e32 v73, v73, v187
	global_store_dword v178, v73, s[28:29] offset:128
	v_cvt_pk_bf16_f32 v187, v73, v73
	global_store_short v179, v187, s[36:37] offset:64
	v_add_u32_e32 v178, 0x32000, v176
	v_add_u32_e32 v179, 0x19000, v177
	v_add_f32_e32 v90, v90, v190
	global_store_dword v178, v90, s[28:29]
	v_cvt_pk_bf16_f32 v190, v90, v90
	global_store_short v179, v190, s[36:37]
	v_add_f32_e32 v74, v74, v191
	global_store_dword v178, v74, s[28:29] offset:128
	v_cvt_pk_bf16_f32 v191, v74, v74
	global_store_short v179, v191, s[36:37] offset:64
	v_add_u32_e32 v178, 0x33000, v176
	v_add_u32_e32 v179, 0x19800, v177
	v_add_f32_e32 v91, v91, v192
	global_store_dword v178, v91, s[28:29]
	v_cvt_pk_bf16_f32 v192, v91, v91
	global_store_short v179, v192, s[36:37]
	v_add_f32_e32 v75, v75, v193
	global_store_dword v178, v75, s[28:29] offset:128
	v_cvt_pk_bf16_f32 v193, v75, v75
	global_store_short v179, v193, s[36:37] offset:64
	v_add_u32_e32 v178, 0x38000, v176
	v_add_u32_e32 v179, 0x1c000, v177
	v_add_f32_e32 v92, v92, v194
	global_store_dword v178, v92, s[28:29]
	v_cvt_pk_bf16_f32 v194, v92, v92
	global_store_short v179, v194, s[36:37]
	v_add_f32_e32 v76, v76, v195
	global_store_dword v178, v76, s[28:29] offset:128
	v_cvt_pk_bf16_f32 v195, v76, v76
	global_store_short v179, v195, s[36:37] offset:64
	v_add_u32_e32 v178, 0x39000, v176
	v_add_u32_e32 v179, 0x1c800, v177
	v_add_f32_e32 v93, v93, v196
	global_store_dword v178, v93, s[28:29]
	v_cvt_pk_bf16_f32 v196, v93, v93
	global_store_short v179, v196, s[36:37]
	v_add_f32_e32 v77, v77, v197
	global_store_dword v178, v77, s[28:29] offset:128
	v_cvt_pk_bf16_f32 v197, v77, v77
	global_store_short v179, v197, s[36:37] offset:64
	v_add_u32_e32 v178, 0x3a000, v176
	v_add_u32_e32 v179, 0x1d000, v177
	v_add_f32_e32 v94, v94, v198
	global_store_dword v178, v94, s[28:29]
	v_cvt_pk_bf16_f32 v198, v94, v94
	global_store_short v179, v198, s[36:37]
	v_add_f32_e32 v78, v78, v199
	global_store_dword v178, v78, s[28:29] offset:128
	v_cvt_pk_bf16_f32 v199, v78, v78
	global_store_short v179, v199, s[36:37] offset:64
	v_add_u32_e32 v178, 0x3b000, v176
	v_add_u32_e32 v179, 0x1d800, v177
	v_add_f32_e32 v95, v95, v200
	global_store_dword v178, v95, s[28:29]
	v_cvt_pk_bf16_f32 v200, v95, v95
	global_store_short v179, v200, s[36:37]
	v_add_f32_e32 v79, v79, v201
	global_store_dword v178, v79, s[28:29] offset:128
	v_cvt_pk_bf16_f32 v201, v79, v79
	global_store_short v179, v201, s[36:37] offset:64
	v_add_u32_e32 v178, 0x60000, v176
	global_load_dword v160, v178, s[28:29]
	global_load_dword v161, v178, s[28:29] offset:128
	v_add_u32_e32 v178, 0x61000, v176
	global_load_dword v162, v178, s[28:29]
	global_load_dword v163, v178, s[28:29] offset:128
	v_add_u32_e32 v178, 0x62000, v176
	global_load_dword v164, v178, s[28:29]
	global_load_dword v165, v178, s[28:29] offset:128
	v_add_u32_e32 v178, 0x63000, v176
	global_load_dword v166, v178, s[28:29]
	global_load_dword v167, v178, s[28:29] offset:128
	v_add_u32_e32 v178, 0x68000, v176
	global_load_dword v168, v178, s[28:29]
	global_load_dword v169, v178, s[28:29] offset:128
	v_add_u32_e32 v178, 0x69000, v176
	global_load_dword v170, v178, s[28:29]
	global_load_dword v171, v178, s[28:29] offset:128
	v_add_u32_e32 v178, 0x6a000, v176
	global_load_dword v172, v178, s[28:29]
	global_load_dword v173, v178, s[28:29] offset:128
	v_add_u32_e32 v178, 0x6b000, v176
	global_load_dword v174, v178, s[28:29]
	global_load_dword v175, v178, s[28:29] offset:128
	v_add_u32_e32 v178, 0x70000, v176
	global_load_dword v184, v178, s[28:29]
	global_load_dword v185, v178, s[28:29] offset:128
	v_add_u32_e32 v178, 0x71000, v176
	global_load_dword v186, v178, s[28:29]
	global_load_dword v187, v178, s[28:29] offset:128
	v_add_u32_e32 v178, 0x72000, v176
	global_load_dword v190, v178, s[28:29]
	global_load_dword v191, v178, s[28:29] offset:128
	v_add_u32_e32 v178, 0x73000, v176
	global_load_dword v192, v178, s[28:29]
	global_load_dword v193, v178, s[28:29] offset:128
	v_add_u32_e32 v178, 0x78000, v176
	global_load_dword v194, v178, s[28:29]
	global_load_dword v195, v178, s[28:29] offset:128
	v_add_u32_e32 v178, 0x79000, v176
	global_load_dword v196, v178, s[28:29]
	global_load_dword v197, v178, s[28:29] offset:128
	v_add_u32_e32 v178, 0x7a000, v176
	global_load_dword v198, v178, s[28:29]
	global_load_dword v199, v178, s[28:29] offset:128
	v_add_u32_e32 v178, 0x7b000, v176
	global_load_dword v200, v178, s[28:29]
	global_load_dword v201, v178, s[28:29] offset:128
	s_waitcnt vmcnt(63)
; DI void phase_resid(const Params& p, const bfu* A, int lda, const bfu* Bt, int K, char* smem) {
;     ...
;     EPI_BEGINM(acc, 4)
;       float* xp = p.out + (size_t)row * 1024 + col;
;       float nv = *xp + v; *xp = nv; p.xb[(size_t)row * 1024 + col] = f2bf(nv);
;     EPI_END
	v_add_u32_e32 v178, 0x40000, v176
	v_add_u32_e32 v179, 0x20000, v177
	v_add_f32_e32 v48, v48, v128
	global_store_dword v178, v48, s[28:29]
	v_cvt_pk_bf16_f32 v128, v48, v48
	global_store_short v179, v128, s[36:37]
	v_add_f32_e32 v32, v32, v129
	global_store_dword v178, v32, s[28:29] offset:128
	v_cvt_pk_bf16_f32 v129, v32, v32
	global_store_short v179, v129, s[36:37] offset:64
	v_add_u32_e32 v178, 0x41000, v176
	v_add_u32_e32 v179, 0x20800, v177
	v_add_f32_e32 v49, v49, v130
	global_store_dword v178, v49, s[28:29]
	v_cvt_pk_bf16_f32 v130, v49, v49
	global_store_short v179, v130, s[36:37]
	v_add_f32_e32 v33, v33, v131
	global_store_dword v178, v33, s[28:29] offset:128
	v_cvt_pk_bf16_f32 v131, v33, v33
	global_store_short v179, v131, s[36:37] offset:64
	v_add_u32_e32 v178, 0x42000, v176
	v_add_u32_e32 v179, 0x21000, v177
	v_add_f32_e32 v50, v50, v132
	global_store_dword v178, v50, s[28:29]
	v_cvt_pk_bf16_f32 v132, v50, v50
	global_store_short v179, v132, s[36:37]
	v_add_f32_e32 v34, v34, v133
	global_store_dword v178, v34, s[28:29] offset:128
	v_cvt_pk_bf16_f32 v133, v34, v34
	global_store_short v179, v133, s[36:37] offset:64
	v_add_u32_e32 v178, 0x43000, v176
	v_add_u32_e32 v179, 0x21800, v177
	v_add_f32_e32 v51, v51, v134
	global_store_dword v178, v51, s[28:29]
	v_cvt_pk_bf16_f32 v134, v51, v51
	global_store_short v179, v134, s[36:37]
	v_add_f32_e32 v35, v35, v135
	global_store_dword v178, v35, s[28:29] offset:128
	v_cvt_pk_bf16_f32 v135, v35, v35
	global_store_short v179, v135, s[36:37] offset:64
	v_add_u32_e32 v178, 0x48000, v176
	v_add_u32_e32 v179, 0x24000, v177
	v_add_f32_e32 v52, v52, v136
	global_store_dword v178, v52, s[28:29]
	v_cvt_pk_bf16_f32 v136, v52, v52
	global_store_short v179, v136, s[36:37]
	v_add_f32_e32 v36, v36, v137
	global_store_dword v178, v36, s[28:29] offset:128
	v_cvt_pk_bf16_f32 v137, v36, v36
	global_store_short v179, v137, s[36:37] offset:64
	v_add_u32_e32 v178, 0x49000, v176
	v_add_u32_e32 v179, 0x24800, v177
	v_add_f32_e32 v53, v53, v138
	global_store_dword v178, v53, s[28:29]
	v_cvt_pk_bf16_f32 v138, v53, v53
	global_store_short v179, v138, s[36:37]
	v_add_f32_e32 v37, v37, v139
	global_store_dword v178, v37, s[28:29] offset:128
	v_cvt_pk_bf16_f32 v139, v37, v37
	global_store_short v179, v139, s[36:37] offset:64
	v_add_u32_e32 v178, 0x4a000, v176
	v_add_u32_e32 v179, 0x25000, v177
	v_add_f32_e32 v54, v54, v140
	global_store_dword v178, v54, s[28:29]
	v_cvt_pk_bf16_f32 v140, v54, v54
	global_store_short v179, v140, s[36:37]
	v_add_f32_e32 v38, v38, v141
	global_store_dword v178, v38, s[28:29] offset:128
	v_cvt_pk_bf16_f32 v141, v38, v38
	global_store_short v179, v141, s[36:37] offset:64
	v_add_u32_e32 v178, 0x4b000, v176
	v_add_u32_e32 v179, 0x25800, v177
	v_add_f32_e32 v55, v55, v142
	global_store_dword v178, v55, s[28:29]
	v_cvt_pk_bf16_f32 v142, v55, v55
	global_store_short v179, v142, s[36:37]
	v_add_f32_e32 v39, v39, v143
	global_store_dword v178, v39, s[28:29] offset:128
	v_cvt_pk_bf16_f32 v143, v39, v39
	global_store_short v179, v143, s[36:37] offset:64
	v_add_u32_e32 v178, 0x50000, v176
	v_add_u32_e32 v179, 0x28000, v177
	v_add_f32_e32 v56, v56, v144
	global_store_dword v178, v56, s[28:29]
	v_cvt_pk_bf16_f32 v144, v56, v56
	global_store_short v179, v144, s[36:37]
	v_add_f32_e32 v40, v40, v145
	global_store_dword v178, v40, s[28:29] offset:128
	v_cvt_pk_bf16_f32 v145, v40, v40
	global_store_short v179, v145, s[36:37] offset:64
	v_add_u32_e32 v178, 0x51000, v176
	v_add_u32_e32 v179, 0x28800, v177
	v_add_f32_e32 v57, v57, v146
	global_store_dword v178, v57, s[28:29]
	v_cvt_pk_bf16_f32 v146, v57, v57
	global_store_short v179, v146, s[36:37]
	v_add_f32_e32 v41, v41, v147
	global_store_dword v178, v41, s[28:29] offset:128
	v_cvt_pk_bf16_f32 v147, v41, v41
	global_store_short v179, v147, s[36:37] offset:64
	v_add_u32_e32 v178, 0x52000, v176
	v_add_u32_e32 v179, 0x29000, v177
	v_add_f32_e32 v58, v58, v148
	global_store_dword v178, v58, s[28:29]
	v_cvt_pk_bf16_f32 v148, v58, v58
	global_store_short v179, v148, s[36:37]
	v_add_f32_e32 v42, v42, v149
	global_store_dword v178, v42, s[28:29] offset:128
	v_cvt_pk_bf16_f32 v149, v42, v42
	global_store_short v179, v149, s[36:37] offset:64
	v_add_u32_e32 v178, 0x53000, v176
	v_add_u32_e32 v179, 0x29800, v177
	v_add_f32_e32 v59, v59, v150
	global_store_dword v178, v59, s[28:29]
	v_cvt_pk_bf16_f32 v150, v59, v59
	global_store_short v179, v150, s[36:37]
	v_add_f32_e32 v43, v43, v151
	global_store_dword v178, v43, s[28:29] offset:128
	v_cvt_pk_bf16_f32 v151, v43, v43
	global_store_short v179, v151, s[36:37] offset:64
	v_add_u32_e32 v178, 0x58000, v176
	v_add_u32_e32 v179, 0x2c000, v177
	v_add_f32_e32 v60, v60, v152
	global_store_dword v178, v60, s[28:29]
	v_cvt_pk_bf16_f32 v152, v60, v60
	global_store_short v179, v152, s[36:37]
	v_add_f32_e32 v44, v44, v153
	global_store_dword v178, v44, s[28:29] offset:128
	v_cvt_pk_bf16_f32 v153, v44, v44
	global_store_short v179, v153, s[36:37] offset:64
	v_add_u32_e32 v178, 0x59000, v176
	v_add_u32_e32 v179, 0x2c800, v177
	v_add_f32_e32 v61, v61, v154
	global_store_dword v178, v61, s[28:29]
	v_cvt_pk_bf16_f32 v154, v61, v61
	global_store_short v179, v154, s[36:37]
	v_add_f32_e32 v45, v45, v155
	global_store_dword v178, v45, s[28:29] offset:128
	v_cvt_pk_bf16_f32 v155, v45, v45
	global_store_short v179, v155, s[36:37] offset:64
	v_add_u32_e32 v178, 0x5a000, v176
	v_add_u32_e32 v179, 0x2d000, v177
	v_add_f32_e32 v62, v62, v156
	global_store_dword v178, v62, s[28:29]
	v_cvt_pk_bf16_f32 v156, v62, v62
	global_store_short v179, v156, s[36:37]
	v_add_f32_e32 v46, v46, v157
	global_store_dword v178, v46, s[28:29] offset:128
	v_cvt_pk_bf16_f32 v157, v46, v46
	global_store_short v179, v157, s[36:37] offset:64
	v_add_u32_e32 v178, 0x5b000, v176
	v_add_u32_e32 v179, 0x2d800, v177
	v_add_f32_e32 v63, v63, v158
	global_store_dword v178, v63, s[28:29]
	v_cvt_pk_bf16_f32 v158, v63, v63
	global_store_short v179, v158, s[36:37]
	v_add_f32_e32 v47, v47, v159
	global_store_dword v178, v47, s[28:29] offset:128
	v_cvt_pk_bf16_f32 v159, v47, v47
	global_store_short v179, v159, s[36:37] offset:64
	s_waitcnt vmcnt(63)
; #define ZERO_ACCM(a, MT) _Pragma("unroll") for (int _m = 0; _m < MT; ++_m) _Pragma("unroll") for (int _n = 0; _n < 2; ++_n) _Pragma("unroll") for (int _i = 0; _i < 16; ++_i) a[_m][_n][_i] = 0.f;
; DI void phase_resid(const Params& p, const bfu* A, int lda, const bfu* Bt, int K, char* smem) {
;     ...
;   for (int id = blockIdx.x; id < 64 * 8; id += gridDim.x) {
;     int tm, tn; map_tile(id, 8, tm, tn);
;     const int m0 = tm * 256, n0 = tn * 128;
;     f32x16 acc[4][2]; ZERO_ACCM(acc, 4)
;     gemm_core<false, false, 4>(A, lda, Bt, K, K, m0, n0, acc, smem);
;     EPI_BEGINM(acc, 4)
;       float* xp = p.out + (size_t)row * 1024 + col;
;       float nv = *xp + v; *xp = nv; p.xb[(size_t)row * 1024 + col] = f2bf(nv);
;     EPI_END
	v_add_u32_e32 v178, 0x60000, v176
	v_add_u32_e32 v179, 0x30000, v177
	v_add_f32_e32 v16, v16, v160
	global_store_dword v178, v16, s[28:29]
	v_cvt_pk_bf16_f32 v160, v16, v16
	global_store_short v179, v160, s[36:37]
	v_add_f32_e32 v0, v0, v161
	global_store_dword v178, v0, s[28:29] offset:128
	v_cvt_pk_bf16_f32 v161, v0, v0
	global_store_short v179, v161, s[36:37] offset:64
	v_add_u32_e32 v178, 0x61000, v176
	v_add_u32_e32 v179, 0x30800, v177
	v_add_f32_e32 v17, v17, v162
	global_store_dword v178, v17, s[28:29]
	v_cvt_pk_bf16_f32 v162, v17, v17
	global_store_short v179, v162, s[36:37]
	v_add_f32_e32 v1, v1, v163
	global_store_dword v178, v1, s[28:29] offset:128
	v_cvt_pk_bf16_f32 v163, v1, v1
	global_store_short v179, v163, s[36:37] offset:64
	v_add_u32_e32 v178, 0x62000, v176
	v_add_u32_e32 v179, 0x31000, v177
	v_add_f32_e32 v18, v18, v164
	global_store_dword v178, v18, s[28:29]
	v_cvt_pk_bf16_f32 v164, v18, v18
	global_store_short v179, v164, s[36:37]
	v_add_f32_e32 v2, v2, v165
	global_store_dword v178, v2, s[28:29] offset:128
	v_cvt_pk_bf16_f32 v165, v2, v2
	global_store_short v179, v165, s[36:37] offset:64
	v_add_u32_e32 v178, 0x63000, v176
	v_add_u32_e32 v179, 0x31800, v177
	v_add_f32_e32 v19, v19, v166
	global_store_dword v178, v19, s[28:29]
	v_cvt_pk_bf16_f32 v166, v19, v19
	global_store_short v179, v166, s[36:37]
	v_add_f32_e32 v3, v3, v167
	global_store_dword v178, v3, s[28:29] offset:128
	v_cvt_pk_bf16_f32 v167, v3, v3
	global_store_short v179, v167, s[36:37] offset:64
	v_add_u32_e32 v178, 0x68000, v176
	v_add_u32_e32 v179, 0x34000, v177
	v_add_f32_e32 v20, v20, v168
	global_store_dword v178, v20, s[28:29]
	v_cvt_pk_bf16_f32 v168, v20, v20
	global_store_short v179, v168, s[36:37]
	v_add_f32_e32 v4, v4, v169
	global_store_dword v178, v4, s[28:29] offset:128
	v_cvt_pk_bf16_f32 v169, v4, v4
	global_store_short v179, v169, s[36:37] offset:64
	v_add_u32_e32 v178, 0x69000, v176
	v_add_u32_e32 v179, 0x34800, v177
	v_add_f32_e32 v21, v21, v170
	global_store_dword v178, v21, s[28:29]
	v_cvt_pk_bf16_f32 v170, v21, v21
	global_store_short v179, v170, s[36:37]
	v_add_f32_e32 v5, v5, v171
	global_store_dword v178, v5, s[28:29] offset:128
	v_cvt_pk_bf16_f32 v171, v5, v5
	global_store_short v179, v171, s[36:37] offset:64
	v_add_u32_e32 v178, 0x6a000, v176
	v_add_u32_e32 v179, 0x35000, v177
	v_add_f32_e32 v22, v22, v172
	global_store_dword v178, v22, s[28:29]
	v_cvt_pk_bf16_f32 v172, v22, v22
	global_store_short v179, v172, s[36:37]
	v_add_f32_e32 v6, v6, v173
	global_store_dword v178, v6, s[28:29] offset:128
	v_cvt_pk_bf16_f32 v173, v6, v6
	global_store_short v179, v173, s[36:37] offset:64
	v_add_u32_e32 v178, 0x6b000, v176
	v_add_u32_e32 v179, 0x35800, v177
	v_add_f32_e32 v23, v23, v174
	global_store_dword v178, v23, s[28:29]
	v_cvt_pk_bf16_f32 v174, v23, v23
	global_store_short v179, v174, s[36:37]
	v_add_f32_e32 v7, v7, v175
	global_store_dword v178, v7, s[28:29] offset:128
	v_cvt_pk_bf16_f32 v175, v7, v7
	global_store_short v179, v175, s[36:37] offset:64
	v_add_u32_e32 v178, 0x70000, v176
	v_add_u32_e32 v179, 0x38000, v177
	v_add_f32_e32 v24, v24, v184
	global_store_dword v178, v24, s[28:29]
	v_cvt_pk_bf16_f32 v184, v24, v24
	global_store_short v179, v184, s[36:37]
	v_add_f32_e32 v8, v8, v185
	global_store_dword v178, v8, s[28:29] offset:128
	v_cvt_pk_bf16_f32 v185, v8, v8
	global_store_short v179, v185, s[36:37] offset:64
	v_add_u32_e32 v178, 0x71000, v176
	v_add_u32_e32 v179, 0x38800, v177
	v_add_f32_e32 v25, v25, v186
	global_store_dword v178, v25, s[28:29]
	v_cvt_pk_bf16_f32 v186, v25, v25
	global_store_short v179, v186, s[36:37]
	v_add_f32_e32 v9, v9, v187
	global_store_dword v178, v9, s[28:29] offset:128
	v_cvt_pk_bf16_f32 v187, v9, v9
	global_store_short v179, v187, s[36:37] offset:64
	v_add_u32_e32 v178, 0x72000, v176
	v_add_u32_e32 v179, 0x39000, v177
	v_add_f32_e32 v26, v26, v190
	global_store_dword v178, v26, s[28:29]
	v_cvt_pk_bf16_f32 v190, v26, v26
	global_store_short v179, v190, s[36:37]
	v_add_f32_e32 v10, v10, v191
	global_store_dword v178, v10, s[28:29] offset:128
	v_cvt_pk_bf16_f32 v191, v10, v10
	global_store_short v179, v191, s[36:37] offset:64
	v_add_u32_e32 v178, 0x73000, v176
	v_add_u32_e32 v179, 0x39800, v177
	v_add_f32_e32 v27, v27, v192
	global_store_dword v178, v27, s[28:29]
	v_cvt_pk_bf16_f32 v192, v27, v27
	global_store_short v179, v192, s[36:37]
	v_add_f32_e32 v11, v11, v193
	global_store_dword v178, v11, s[28:29] offset:128
	v_cvt_pk_bf16_f32 v193, v11, v11
	global_store_short v179, v193, s[36:37] offset:64
	v_add_u32_e32 v178, 0x78000, v176
	v_add_u32_e32 v179, 0x3c000, v177
	v_add_f32_e32 v28, v28, v194
	global_store_dword v178, v28, s[28:29]
	v_cvt_pk_bf16_f32 v194, v28, v28
	global_store_short v179, v194, s[36:37]
	v_add_f32_e32 v12, v12, v195
	global_store_dword v178, v12, s[28:29] offset:128
	v_cvt_pk_bf16_f32 v195, v12, v12
	global_store_short v179, v195, s[36:37] offset:64
	v_add_u32_e32 v178, 0x79000, v176
	v_add_u32_e32 v179, 0x3c800, v177
	v_add_f32_e32 v29, v29, v196
	global_store_dword v178, v29, s[28:29]
	v_cvt_pk_bf16_f32 v196, v29, v29
	global_store_short v179, v196, s[36:37]
	v_add_f32_e32 v13, v13, v197
	global_store_dword v178, v13, s[28:29] offset:128
	v_cvt_pk_bf16_f32 v197, v13, v13
	global_store_short v179, v197, s[36:37] offset:64
	v_add_u32_e32 v178, 0x7a000, v176
	v_add_u32_e32 v179, 0x3d000, v177
	v_add_f32_e32 v30, v30, v198
	global_store_dword v178, v30, s[28:29]
	v_cvt_pk_bf16_f32 v198, v30, v30
	global_store_short v179, v198, s[36:37]
	v_add_f32_e32 v14, v14, v199
	global_store_dword v178, v14, s[28:29] offset:128
	v_cvt_pk_bf16_f32 v199, v14, v14
	global_store_short v179, v199, s[36:37] offset:64
	v_add_u32_e32 v178, 0x7b000, v176
	v_add_u32_e32 v179, 0x3d800, v177
	v_add_f32_e32 v31, v31, v200
	global_store_dword v178, v31, s[28:29]
	v_cvt_pk_bf16_f32 v200, v31, v31
	global_store_short v179, v200, s[36:37]
	v_add_f32_e32 v15, v15, v201
	global_store_dword v178, v15, s[28:29] offset:128
	v_cvt_pk_bf16_f32 v201, v15, v15
	global_store_short v179, v201, s[36:37] offset:64
	s_load_dword s3, s[4:5], 0x0
	s_waitcnt lgkmcnt(0)
	s_add_i32 s2, s3, s2
	s_cmpk_gt_i32 s2, 0x1ff
	s_cbranch_scc0 .LBB0_95

; template <bool NORM, bool DEEP, int MTW, int KSEG, class HOOK>
; DI void gemm_core_h(const bfu* __restrict__ A, int lda, const bfu* __restrict__ Bt, int ldb, int K, int m0, int n0,
;                     f32x16 (&acc)[MTW][2], char* smem, HOOK hook) {
;     ...
;   if (DEEP) {
;     for (int kt = 0; kt < nk; kt += 2) {
;       GEMM_STEP(ra0, rb0, kt, 2)
;       GEMM_STEP(ra1, rb1, kt + 1, 2)
;     }
;   } else {
;     for (int kt = 0; kt < nk; ++kt) {
;       GEMM_STEP(ra0, rb0, kt, 1)
;       if (KSEG > 0) { if (((kt + 1) % (KSEG > 0 ? KSEG : 1)) == 0) hook((kt + 1) / (KSEG > 0 ? KSEG : 1) - 1); }
;     }
.LBB0_128:
	s_waitcnt lgkmcnt(0)
	s_barrier
	s_waitcnt vmcnt(7)
	ds_write_b128 v183, v[148:151]
	s_waitcnt vmcnt(6)
	ds_write_b128 v183, v[144:147] offset:4608
	s_waitcnt vmcnt(5)
	ds_write_b128 v183, v[156:159] offset:9216
	s_waitcnt vmcnt(4)
	ds_write_b128 v183, v[152:155] offset:13824
	s_waitcnt vmcnt(3)
	ds_write_b128 v183, v[164:167] offset:18432
	s_waitcnt vmcnt(2)
	ds_write_b128 v183, v[160:163] offset:23040
	s_waitcnt vmcnt(1)
	ds_write_b128 v183, v[168:171] offset:27648
	s_waitcnt vmcnt(0)
	ds_write_b128 v183, v[172:175] offset:32256
	ds_write_b128 v183, v[140:143] offset:36864
	ds_write_b128 v183, v[136:139] offset:41472
	ds_write_b128 v183, v[128:131] offset:46080
	ds_write_b128 v183, v[132:135] offset:50688
	s_waitcnt lgkmcnt(0)
	s_barrier
	ds_read_b128 v[128:131], v179
	ds_read_b128 v[132:135], v182 offset:36864
	ds_read_b128 v[136:139], v182 offset:36896
	ds_read_b128 v[140:143], v179 offset:32
	ds_read_b128 v[144:147], v182 offset:41472
	ds_read_b128 v[148:151], v182 offset:41504
	s_waitcnt lgkmcnt(4)
	v_mfma_f32_32x32x16_bf16 v[112:127], v[128:131], v[132:135], v[112:127]
	s_waitcnt lgkmcnt(1)
	v_mfma_f32_32x32x16_bf16 v[96:111], v[128:131], v[144:147], v[96:111]
	ds_read_b128 v[128:131], v179 offset:4608
	ds_read_b128 v[152:155], v179 offset:4640
	s_waitcnt lgkmcnt(1)
	v_mfma_f32_32x32x16_bf16 v[80:95], v[128:131], v[132:135], v[80:95]
	v_mfma_f32_32x32x16_bf16 v[64:79], v[128:131], v[144:147], v[64:79]
	ds_read_b128 v[128:131], v179 offset:9216
	ds_read_b128 v[156:159], v179 offset:9248
	s_waitcnt lgkmcnt(1)
	v_mfma_f32_32x32x16_bf16 v[48:63], v[128:131], v[132:135], v[48:63]
	v_mfma_f32_32x32x16_bf16 v[32:47], v[128:131], v[144:147], v[32:47]
	ds_read_b128 v[128:131], v177
	ds_read_b128 v[160:163], v177 offset:32
	s_waitcnt lgkmcnt(1)
	v_mfma_f32_32x32x16_bf16 v[16:31], v[128:131], v[132:135], v[16:31]
	v_mfma_f32_32x32x16_bf16 v[0:15], v[128:131], v[144:147], v[0:15]
	v_mfma_f32_32x32x16_bf16 v[112:127], v[140:143], v[136:139], v[112:127]
	v_mfma_f32_32x32x16_bf16 v[96:111], v[140:143], v[148:151], v[96:111]
	v_mfma_f32_32x32x16_bf16 v[80:95], v[152:155], v[136:139], v[80:95]
	v_mfma_f32_32x32x16_bf16 v[64:79], v[152:155], v[148:151], v[64:79]
	v_mfma_f32_32x32x16_bf16 v[48:63], v[156:159], v[136:139], v[48:63]
	s_waitcnt lgkmcnt(0)
	v_mfma_f32_32x32x16_bf16 v[16:31], v[160:163], v[136:139], v[16:31]
	ds_read_b128 v[128:131], v179 offset:64
	ds_read_b128 v[132:135], v182 offset:36928
	ds_read_b128 v[184:187], v182 offset:36960
	ds_read_b128 v[136:139], v179 offset:96
	ds_read_b128 v[140:143], v182 offset:41536
	ds_read_b128 v[190:193], v182 offset:41568
	v_mfma_f32_32x32x16_bf16 v[32:47], v[156:159], v[148:151], v[32:47]
	v_mfma_f32_32x32x16_bf16 v[0:15], v[160:163], v[148:151], v[0:15]
	s_waitcnt lgkmcnt(4)
	v_mfma_f32_32x32x16_bf16 v[112:127], v[128:131], v[132:135], v[112:127]
	s_waitcnt lgkmcnt(1)
	v_mfma_f32_32x32x16_bf16 v[96:111], v[128:131], v[140:143], v[96:111]
	ds_read_b128 v[128:131], v179 offset:4672
	ds_read_b128 v[160:163], v179 offset:4704
	s_waitcnt lgkmcnt(1)
	v_mfma_f32_32x32x16_bf16 v[80:95], v[128:131], v[132:135], v[80:95]
	v_mfma_f32_32x32x16_bf16 v[64:79], v[128:131], v[140:143], v[64:79]
	ds_read_b128 v[128:131], v179 offset:9280
	ds_read_b128 v[194:197], v179 offset:9312
	s_waitcnt lgkmcnt(1)
	v_mfma_f32_32x32x16_bf16 v[48:63], v[128:131], v[132:135], v[48:63]
	v_mfma_f32_32x32x16_bf16 v[32:47], v[128:131], v[140:143], v[32:47]
	ds_read_b128 v[128:131], v177 offset:64
	ds_read_b128 v[198:201], v177 offset:96
	s_waitcnt lgkmcnt(1)
	v_mfma_f32_32x32x16_bf16 v[16:31], v[128:131], v[132:135], v[16:31]
	v_add_u32_e32 v132, s5, v176
	v_add_u32_e32 v188, 64, v132
	v_add_u32_e32 v133, s5, v178
	s_add_i32 s5, s5, 64
	s_cmpk_lg_i32 s5, 0x3c0
	v_mfma_f32_32x32x16_bf16 v[0:15], v[128:131], v[140:143], v[0:15]
	v_lshl_add_u64 v[128:129], v[188:189], 1, s[76:77]
	v_add_u32_e32 v188, 0x8040, v132
	v_lshl_add_u64 v[130:131], v[188:189], 1, s[76:77]
	v_add_u32_e32 v188, 0x10040, v132
	global_load_dwordx4 v[148:151], v[128:129], off
	global_load_dwordx4 v[144:147], v[130:131], off
	v_lshl_add_u64 v[128:129], v[188:189], 1, s[76:77]
	v_add_u32_e32 v188, 0x18040, v132
	v_lshl_add_u64 v[130:131], v[188:189], 1, s[76:77]
	v_add_u32_e32 v188, 0x20040, v132
	global_load_dwordx4 v[156:159], v[128:129], off
	global_load_dwordx4 v[152:155], v[130:131], off
	v_lshl_add_u64 v[128:129], v[188:189], 1, s[76:77]
	v_add_u32_e32 v188, 0x28040, v132
	v_lshl_add_u64 v[130:131], v[188:189], 1, s[76:77]
	v_add_u32_e32 v188, 0x30040, v132
	v_mfma_f32_32x32x16_bf16 v[80:95], v[160:163], v[184:187], v[80:95]
	v_mfma_f32_32x32x16_bf16 v[64:79], v[160:163], v[190:193], v[64:79]
	global_load_dwordx4 v[164:167], v[128:129], off
	global_load_dwordx4 v[160:163], v[130:131], off
	v_lshl_add_u64 v[128:129], v[188:189], 1, s[76:77]
	v_add_u32_e32 v188, 0x38040, v132
	v_lshl_add_u64 v[130:131], v[188:189], 1, s[76:77]
	v_add_u32_e32 v188, 64, v133
	global_load_dwordx4 v[168:171], v[128:129], off
	global_load_dwordx4 v[172:175], v[130:131], off
	v_lshl_add_u64 v[128:129], v[188:189], 1, s[22:23]
	v_add_u32_e32 v188, 0x8040, v133
	v_lshl_add_u64 v[130:131], v[188:189], 1, s[22:23]
	v_add_u32_e32 v188, 0x10040, v133
	v_mfma_f32_32x32x16_bf16 v[112:127], v[136:139], v[184:187], v[112:127]
	v_mfma_f32_32x32x16_bf16 v[96:111], v[136:139], v[190:193], v[96:111]
	global_load_dwordx4 v[140:143], v[128:129], off
	global_load_dwordx4 v[136:139], v[130:131], off
	v_lshl_add_u64 v[128:129], v[188:189], 1, s[22:23]
	v_add_u32_e32 v188, 0x18040, v133
	v_lshl_add_u64 v[132:133], v[188:189], 1, s[22:23]
	global_load_dwordx4 v[128:131], v[128:129], off
	s_nop 0
	global_load_dwordx4 v[132:135], v[132:133], off
	v_mfma_f32_32x32x16_bf16 v[48:63], v[194:197], v[184:187], v[48:63]
	v_mfma_f32_32x32x16_bf16 v[32:47], v[194:197], v[190:193], v[32:47]
	s_waitcnt lgkmcnt(0)
	v_mfma_f32_32x32x16_bf16 v[16:31], v[198:201], v[184:187], v[16:31]
	v_mfma_f32_32x32x16_bf16 v[0:15], v[198:201], v[190:193], v[0:15]
	s_cbranch_scc1 .LBB0_128
	s_waitcnt lgkmcnt(0)
	s_barrier
	s_waitcnt vmcnt(11)
	ds_write_b128 v183, v[148:151]
	s_waitcnt vmcnt(10)
	ds_write_b128 v183, v[144:147] offset:4608
	s_waitcnt vmcnt(9)
	ds_write_b128 v183, v[156:159] offset:9216
	s_waitcnt vmcnt(8)
	ds_write_b128 v183, v[152:155] offset:13824
	s_waitcnt vmcnt(7)
	ds_write_b128 v183, v[164:167] offset:18432
	s_waitcnt vmcnt(6)
	ds_write_b128 v183, v[160:163] offset:23040
	s_waitcnt vmcnt(5)
	ds_write_b128 v183, v[168:171] offset:27648
	s_waitcnt vmcnt(4)
	ds_write_b128 v183, v[172:175] offset:32256
	s_waitcnt vmcnt(3)
	ds_write_b128 v183, v[140:143] offset:36864
	s_waitcnt vmcnt(2)
	ds_write_b128 v183, v[136:139] offset:41472
	s_waitcnt vmcnt(1)
	ds_write_b128 v183, v[128:131] offset:46080
	s_waitcnt vmcnt(0)
	ds_write_b128 v183, v[132:135] offset:50688
	s_waitcnt lgkmcnt(0)
	s_barrier
	ds_read_b128 v[128:131], v182 offset:41472
	ds_read_b128 v[132:135], v182 offset:36864
	ds_read_b128 v[136:139], v182 offset:36896
	ds_read_b128 v[140:143], v179
	ds_read_b128 v[144:147], v179 offset:32
	s_waitcnt lgkmcnt(1)
	v_mfma_f32_32x32x16_bf16 v[112:127], v[140:143], v[132:135], v[112:127]
	v_readlane_b32 s16, v253, 32
	v_readlane_b32 s28, v253, 44
	v_readlane_b32 s29, v253, 45
	v_readlane_b32 s17, v253, 33
	v_readlane_b32 s18, v253, 34
	v_readlane_b32 s19, v253, 35
	v_readlane_b32 s20, v253, 36
	v_mfma_f32_32x32x16_bf16 v[96:111], v[140:143], v[128:131], v[96:111]
	ds_read_b128 v[140:143], v179 offset:4608
	v_readlane_b32 s21, v253, 37
	v_readlane_b32 s22, v253, 38
	v_readlane_b32 s23, v253, 39
	v_readlane_b32 s24, v253, 40
	v_readlane_b32 s25, v253, 41
	v_readlane_b32 s26, v253, 42
	s_waitcnt lgkmcnt(0)
	v_mfma_f32_32x32x16_bf16 v[80:95], v[140:143], v[132:135], v[80:95]
	v_readlane_b32 s27, v253, 43
	v_readlane_b32 s30, v253, 46
	v_readlane_b32 s31, v253, 47
	v_mfma_f32_32x32x16_bf16 v[64:79], v[140:143], v[128:131], v[64:79]
	ds_read_b128 v[140:143], v179 offset:9216
	s_waitcnt lgkmcnt(0)
	v_mfma_f32_32x32x16_bf16 v[48:63], v[140:143], v[132:135], v[48:63]
	v_mfma_f32_32x32x16_bf16 v[32:47], v[140:143], v[128:131], v[32:47]
	ds_read_b128 v[140:143], v177
	ds_read_b128 v[148:151], v177 offset:32
	s_waitcnt lgkmcnt(1)
	v_mfma_f32_32x32x16_bf16 v[16:31], v[140:143], v[132:135], v[16:31]
	ds_read_b128 v[132:135], v179 offset:4640
	v_mfma_f32_32x32x16_bf16 v[0:15], v[140:143], v[128:131], v[0:15]
	ds_read_b128 v[128:131], v182 offset:41504
	s_waitcnt lgkmcnt(1)
	v_mfma_f32_32x32x16_bf16 v[80:95], v[132:135], v[136:139], v[80:95]
	s_waitcnt lgkmcnt(0)
	v_mfma_f32_32x32x16_bf16 v[64:79], v[132:135], v[128:131], v[64:79]
	ds_read_b128 v[132:135], v179 offset:9248
	v_mfma_f32_32x32x16_bf16 v[112:127], v[144:147], v[136:139], v[112:127]
	v_mfma_f32_32x32x16_bf16 v[96:111], v[144:147], v[128:131], v[96:111]
	s_waitcnt lgkmcnt(0)
	v_mfma_f32_32x32x16_bf16 v[48:63], v[132:135], v[136:139], v[48:63]
	v_mfma_f32_32x32x16_bf16 v[32:47], v[132:135], v[128:131], v[32:47]
	v_mfma_f32_32x32x16_bf16 v[16:31], v[148:151], v[136:139], v[16:31]
	v_mfma_f32_32x32x16_bf16 v[0:15], v[148:151], v[128:131], v[0:15]
	ds_read_b128 v[128:131], v182 offset:36928
	ds_read_b128 v[132:135], v182 offset:41536
	ds_read_b128 v[136:139], v179 offset:64
	s_waitcnt lgkmcnt(0)
	v_mfma_f32_32x32x16_bf16 v[112:127], v[136:139], v[128:131], v[112:127]
	v_mfma_f32_32x32x16_bf16 v[96:111], v[136:139], v[132:135], v[96:111]
	ds_read_b128 v[136:139], v179 offset:4672
	s_waitcnt lgkmcnt(0)
	v_mfma_f32_32x32x16_bf16 v[80:95], v[136:139], v[128:131], v[80:95]
	v_mfma_f32_32x32x16_bf16 v[64:79], v[136:139], v[132:135], v[64:79]
	ds_read_b128 v[136:139], v179 offset:9280
	s_waitcnt lgkmcnt(0)
	v_mfma_f32_32x32x16_bf16 v[48:63], v[136:139], v[128:131], v[48:63]
	v_mfma_f32_32x32x16_bf16 v[32:47], v[136:139], v[132:135], v[32:47]
	ds_read_b128 v[136:139], v177 offset:64
	s_waitcnt lgkmcnt(0)
	v_mfma_f32_32x32x16_bf16 v[16:31], v[136:139], v[128:131], v[16:31]
	v_mfma_f32_32x32x16_bf16 v[0:15], v[136:139], v[132:135], v[0:15]
	ds_read_b128 v[128:131], v182 offset:36960
	ds_read_b128 v[132:135], v182 offset:41568
	ds_read_b128 v[136:139], v179 offset:96
	s_waitcnt lgkmcnt(0)
	v_mfma_f32_32x32x16_bf16 v[112:127], v[136:139], v[128:131], v[112:127]
	v_mfma_f32_32x32x16_bf16 v[96:111], v[136:139], v[132:135], v[96:111]
	ds_read_b128 v[136:139], v179 offset:4704
	s_waitcnt lgkmcnt(0)
	v_mfma_f32_32x32x16_bf16 v[80:95], v[136:139], v[128:131], v[80:95]
	v_mfma_f32_32x32x16_bf16 v[64:79], v[136:139], v[132:135], v[64:79]
	ds_read_b128 v[136:139], v179 offset:9312
	s_waitcnt lgkmcnt(0)
	v_mfma_f32_32x32x16_bf16 v[48:63], v[136:139], v[128:131], v[48:63]
	v_mfma_f32_32x32x16_bf16 v[32:47], v[136:139], v[132:135], v[32:47]
	ds_read_b128 v[136:139], v177 offset:96
	s_waitcnt lgkmcnt(0)
	s_barrier
; #define ZERO_ACCM(a, MT) _Pragma("unroll") for (int _m = 0; _m < MT; ++_m) _Pragma("unroll") for (int _n = 0; _n < 2; ++_n) _Pragma("unroll") for (int _i = 0; _i < 16; ++_i) a[_m][_n][_i] = 0.f;
; DI void phase_resid(const Params& p, const bfu* A, int lda, const bfu* Bt, int K, char* smem) {
;   GEMM_IDS
;   for (int id = blockIdx.x; id < 64 * 8; id += gridDim.x) {
;     int tm, tn; map_tile(id, 8, tm, tn);
;     const int m0 = tm * 256, n0 = tn * 128;
;     f32x16 acc[4][2]; ZERO_ACCM(acc, 4)
;     gemm_core<false, false, 4>(A, lda, Bt, K, K, m0, n0, acc, smem);
;     EPI_BEGINM(acc, 4)
;       float* xp = p.out + (size_t)row * 1024 + col;
;       float nv = *xp + v; *xp = nv; p.xb[(size_t)row * 1024 + col] = f2bf(nv);
;     EPI_END
;   }
	v_mfma_f32_32x32x16_bf16 v[16:31], v[136:139], v[128:131], v[16:31]
	v_mfma_f32_32x32x16_bf16 v[0:15], v[136:139], v[132:135], v[0:15]
	v_add_u32_e32 v176, s3, v180
	v_or_b32_e32 v177, s4, v181
	v_lshlrev_b32_e32 v176, 12, v176
	v_lshl_add_u32 v176, v177, 2, v176
	v_lshrrev_b32_e32 v177, 1, v176
	v_readlane_b32 s4, v254, 38
	v_readlane_b32 s5, v254, 39
	global_load_dword v128, v176, s[28:29]
	global_load_dword v129, v176, s[28:29] offset:128
	v_add_u32_e32 v178, 0x1000, v176
	global_load_dword v130, v178, s[28:29]
	global_load_dword v131, v178, s[28:29] offset:128
	v_add_u32_e32 v178, 0x2000, v176
	global_load_dword v132, v178, s[28:29]
	global_load_dword v133, v178, s[28:29] offset:128
	v_add_u32_e32 v178, 0x3000, v176
	global_load_dword v134, v178, s[28:29]
	global_load_dword v135, v178, s[28:29] offset:128
	v_add_u32_e32 v178, 0x8000, v176
	global_load_dword v136, v178, s[28:29]
	global_load_dword v137, v178, s[28:29] offset:128
	v_add_u32_e32 v178, 0x9000, v176
	global_load_dword v138, v178, s[28:29]
	global_load_dword v139, v178, s[28:29] offset:128
	v_add_u32_e32 v178, 0xa000, v176
	global_load_dword v140, v178, s[28:29]
	global_load_dword v141, v178, s[28:29] offset:128
	v_add_u32_e32 v178, 0xb000, v176
	global_load_dword v142, v178, s[28:29]
	global_load_dword v143, v178, s[28:29] offset:128
	v_add_u32_e32 v178, 0x10000, v176
	global_load_dword v144, v178, s[28:29]
	global_load_dword v145, v178, s[28:29] offset:128
	v_add_u32_e32 v178, 0x11000, v176
	global_load_dword v146, v178, s[28:29]
	global_load_dword v147, v178, s[28:29] offset:128
	v_add_u32_e32 v178, 0x12000, v176
	global_load_dword v148, v178, s[28:29]
	global_load_dword v149, v178, s[28:29] offset:128
	v_add_u32_e32 v178, 0x13000, v176
	global_load_dword v150, v178, s[28:29]
	global_load_dword v151, v178, s[28:29] offset:128
	v_add_u32_e32 v178, 0x18000, v176
	global_load_dword v152, v178, s[28:29]
	global_load_dword v153, v178, s[28:29] offset:128
	v_add_u32_e32 v178, 0x19000, v176
	global_load_dword v154, v178, s[28:29]
	global_load_dword v155, v178, s[28:29] offset:128
	v_add_u32_e32 v178, 0x1a000, v176
	global_load_dword v156, v178, s[28:29]
	global_load_dword v157, v178, s[28:29] offset:128
	v_add_u32_e32 v178, 0x1b000, v176
	global_load_dword v158, v178, s[28:29]
	global_load_dword v159, v178, s[28:29] offset:128
	v_add_u32_e32 v178, 0x20000, v176
	global_load_dword v160, v178, s[28:29]
	global_load_dword v161, v178, s[28:29] offset:128
	v_add_u32_e32 v178, 0x21000, v176
	global_load_dword v162, v178, s[28:29]
	global_load_dword v163, v178, s[28:29] offset:128
	v_add_u32_e32 v178, 0x22000, v176
	global_load_dword v164, v178, s[28:29]
	global_load_dword v165, v178, s[28:29] offset:128
	v_add_u32_e32 v178, 0x23000, v176
	global_load_dword v166, v178, s[28:29]
	global_load_dword v167, v178, s[28:29] offset:128
	v_add_u32_e32 v178, 0x28000, v176
	global_load_dword v168, v178, s[28:29]
	global_load_dword v169, v178, s[28:29] offset:128
	v_add_u32_e32 v178, 0x29000, v176
	global_load_dword v170, v178, s[28:29]
	global_load_dword v171, v178, s[28:29] offset:128
	v_add_u32_e32 v178, 0x2a000, v176
	global_load_dword v172, v178, s[28:29]
	global_load_dword v173, v178, s[28:29] offset:128
	v_add_u32_e32 v178, 0x2b000, v176
	global_load_dword v174, v178, s[28:29]
	global_load_dword v175, v178, s[28:29] offset:128
	v_add_u32_e32 v178, 0x30000, v176
	global_load_dword v184, v178, s[28:29]
	global_load_dword v185, v178, s[28:29] offset:128
	v_add_u32_e32 v178, 0x31000, v176
	global_load_dword v186, v178, s[28:29]
	global_load_dword v187, v178, s[28:29] offset:128
	v_add_u32_e32 v178, 0x32000, v176
	global_load_dword v190, v178, s[28:29]
	global_load_dword v191, v178, s[28:29] offset:128
	v_add_u32_e32 v178, 0x33000, v176
	global_load_dword v192, v178, s[28:29]
	global_load_dword v193, v178, s[28:29] offset:128
	v_add_u32_e32 v178, 0x38000, v176
	global_load_dword v194, v178, s[28:29]
	global_load_dword v195, v178, s[28:29] offset:128
	v_add_u32_e32 v178, 0x39000, v176
	global_load_dword v196, v178, s[28:29]
	global_load_dword v197, v178, s[28:29] offset:128
	v_add_u32_e32 v178, 0x3a000, v176
	global_load_dword v198, v178, s[28:29]
	global_load_dword v199, v178, s[28:29] offset:128
	v_add_u32_e32 v178, 0x3b000, v176
	global_load_dword v200, v178, s[28:29]
	global_load_dword v201, v178, s[28:29] offset:128
	s_waitcnt vmcnt(32)
; DI void phase_resid(const Params& p, const bfu* A, int lda, const bfu* Bt, int K, char* smem) {
;     ...
;     EPI_BEGINM(acc, 4)
;       float* xp = p.out + (size_t)row * 1024 + col;
;       float nv = *xp + v; *xp = nv; p.xb[(size_t)row * 1024 + col] = f2bf(nv);
;     EPI_END
	v_add_f32_e32 v112, v112, v128
	global_store_dword v176, v112, s[28:29]
	v_cvt_pk_bf16_f32 v128, v112, v112
	global_store_short v177, v128, s[36:37]
	v_add_f32_e32 v96, v96, v129
	global_store_dword v176, v96, s[28:29] offset:128
	v_cvt_pk_bf16_f32 v129, v96, v96
	global_store_short v177, v129, s[36:37] offset:64
	v_add_u32_e32 v178, 0x1000, v176
	v_add_u32_e32 v179, 0x800, v177
	v_add_f32_e32 v113, v113, v130
	global_store_dword v178, v113, s[28:29]
	v_cvt_pk_bf16_f32 v130, v113, v113
	global_store_short v179, v130, s[36:37]
	v_add_f32_e32 v97, v97, v131
	global_store_dword v178, v97, s[28:29] offset:128
	v_cvt_pk_bf16_f32 v131, v97, v97
	global_store_short v179, v131, s[36:37] offset:64
	v_add_u32_e32 v178, 0x2000, v176
	v_add_u32_e32 v179, 0x1000, v177
	v_add_f32_e32 v114, v114, v132
	global_store_dword v178, v114, s[28:29]
	v_cvt_pk_bf16_f32 v132, v114, v114
	global_store_short v179, v132, s[36:37]
	v_add_f32_e32 v98, v98, v133
	global_store_dword v178, v98, s[28:29] offset:128
	v_cvt_pk_bf16_f32 v133, v98, v98
	global_store_short v179, v133, s[36:37] offset:64
	v_add_u32_e32 v178, 0x3000, v176
	v_add_u32_e32 v179, 0x1800, v177
	v_add_f32_e32 v115, v115, v134
	global_store_dword v178, v115, s[28:29]
	v_cvt_pk_bf16_f32 v134, v115, v115
	global_store_short v179, v134, s[36:37]
	v_add_f32_e32 v99, v99, v135
	global_store_dword v178, v99, s[28:29] offset:128
	v_cvt_pk_bf16_f32 v135, v99, v99
	global_store_short v179, v135, s[36:37] offset:64
	v_add_u32_e32 v178, 0x8000, v176
	v_add_u32_e32 v179, 0x4000, v177
	v_add_f32_e32 v116, v116, v136
	global_store_dword v178, v116, s[28:29]
	v_cvt_pk_bf16_f32 v136, v116, v116
	global_store_short v179, v136, s[36:37]
	v_add_f32_e32 v100, v100, v137
	global_store_dword v178, v100, s[28:29] offset:128
	v_cvt_pk_bf16_f32 v137, v100, v100
	global_store_short v179, v137, s[36:37] offset:64
	v_add_u32_e32 v178, 0x9000, v176
	v_add_u32_e32 v179, 0x4800, v177
	v_add_f32_e32 v117, v117, v138
	global_store_dword v178, v117, s[28:29]
	v_cvt_pk_bf16_f32 v138, v117, v117
	global_store_short v179, v138, s[36:37]
	v_add_f32_e32 v101, v101, v139
	global_store_dword v178, v101, s[28:29] offset:128
	v_cvt_pk_bf16_f32 v139, v101, v101
	global_store_short v179, v139, s[36:37] offset:64
	v_add_u32_e32 v178, 0xa000, v176
	v_add_u32_e32 v179, 0x5000, v177
	v_add_f32_e32 v118, v118, v140
	global_store_dword v178, v118, s[28:29]
	v_cvt_pk_bf16_f32 v140, v118, v118
	global_store_short v179, v140, s[36:37]
	v_add_f32_e32 v102, v102, v141
	global_store_dword v178, v102, s[28:29] offset:128
	v_cvt_pk_bf16_f32 v141, v102, v102
	global_store_short v179, v141, s[36:37] offset:64
	v_add_u32_e32 v178, 0xb000, v176
	v_add_u32_e32 v179, 0x5800, v177
	v_add_f32_e32 v119, v119, v142
	global_store_dword v178, v119, s[28:29]
	v_cvt_pk_bf16_f32 v142, v119, v119
	global_store_short v179, v142, s[36:37]
	v_add_f32_e32 v103, v103, v143
	global_store_dword v178, v103, s[28:29] offset:128
	v_cvt_pk_bf16_f32 v143, v103, v103
	global_store_short v179, v143, s[36:37] offset:64
	v_add_u32_e32 v178, 0x10000, v176
	v_add_u32_e32 v179, 0x8000, v177
	v_add_f32_e32 v120, v120, v144
	global_store_dword v178, v120, s[28:29]
	v_cvt_pk_bf16_f32 v144, v120, v120
	global_store_short v179, v144, s[36:37]
	v_add_f32_e32 v104, v104, v145
	global_store_dword v178, v104, s[28:29] offset:128
	v_cvt_pk_bf16_f32 v145, v104, v104
	global_store_short v179, v145, s[36:37] offset:64
	v_add_u32_e32 v178, 0x11000, v176
	v_add_u32_e32 v179, 0x8800, v177
	v_add_f32_e32 v121, v121, v146
	global_store_dword v178, v121, s[28:29]
	v_cvt_pk_bf16_f32 v146, v121, v121
	global_store_short v179, v146, s[36:37]
	v_add_f32_e32 v105, v105, v147
	global_store_dword v178, v105, s[28:29] offset:128
	v_cvt_pk_bf16_f32 v147, v105, v105
	global_store_short v179, v147, s[36:37] offset:64
	v_add_u32_e32 v178, 0x12000, v176
	v_add_u32_e32 v179, 0x9000, v177
	v_add_f32_e32 v122, v122, v148
	global_store_dword v178, v122, s[28:29]
	v_cvt_pk_bf16_f32 v148, v122, v122
	global_store_short v179, v148, s[36:37]
	v_add_f32_e32 v106, v106, v149
	global_store_dword v178, v106, s[28:29] offset:128
	v_cvt_pk_bf16_f32 v149, v106, v106
	global_store_short v179, v149, s[36:37] offset:64
	v_add_u32_e32 v178, 0x13000, v176
	v_add_u32_e32 v179, 0x9800, v177
	v_add_f32_e32 v123, v123, v150
	global_store_dword v178, v123, s[28:29]
	v_cvt_pk_bf16_f32 v150, v123, v123
	global_store_short v179, v150, s[36:37]
	v_add_f32_e32 v107, v107, v151
	global_store_dword v178, v107, s[28:29] offset:128
	v_cvt_pk_bf16_f32 v151, v107, v107
	global_store_short v179, v151, s[36:37] offset:64
	v_add_u32_e32 v178, 0x18000, v176
	v_add_u32_e32 v179, 0xc000, v177
	v_add_f32_e32 v124, v124, v152
	global_store_dword v178, v124, s[28:29]
	v_cvt_pk_bf16_f32 v152, v124, v124
	global_store_short v179, v152, s[36:37]
	v_add_f32_e32 v108, v108, v153
	global_store_dword v178, v108, s[28:29] offset:128
	v_cvt_pk_bf16_f32 v153, v108, v108
	global_store_short v179, v153, s[36:37] offset:64
	v_add_u32_e32 v178, 0x19000, v176
	v_add_u32_e32 v179, 0xc800, v177
	v_add_f32_e32 v125, v125, v154
	global_store_dword v178, v125, s[28:29]
	v_cvt_pk_bf16_f32 v154, v125, v125
	global_store_short v179, v154, s[36:37]
	v_add_f32_e32 v109, v109, v155
	global_store_dword v178, v109, s[28:29] offset:128
	v_cvt_pk_bf16_f32 v155, v109, v109
	global_store_short v179, v155, s[36:37] offset:64
	v_add_u32_e32 v178, 0x1a000, v176
	v_add_u32_e32 v179, 0xd000, v177
	v_add_f32_e32 v126, v126, v156
	global_store_dword v178, v126, s[28:29]
	v_cvt_pk_bf16_f32 v156, v126, v126
	global_store_short v179, v156, s[36:37]
	v_add_f32_e32 v110, v110, v157
; DI void phase_resid(const Params& p, const bfu* A, int lda, const bfu* Bt, int K, char* smem) {
;     ...
;     EPI_BEGINM(acc, 4)
;       float* xp = p.out + (size_t)row * 1024 + col;
;       float nv = *xp + v; *xp = nv; p.xb[(size_t)row * 1024 + col] = f2bf(nv);
;     EPI_END
	global_store_dword v178, v110, s[28:29] offset:128
	v_cvt_pk_bf16_f32 v157, v110, v110
	global_store_short v179, v157, s[36:37] offset:64
	v_add_u32_e32 v178, 0x1b000, v176
	v_add_u32_e32 v179, 0xd800, v177
	v_add_f32_e32 v127, v127, v158
	global_store_dword v178, v127, s[28:29]
	v_cvt_pk_bf16_f32 v158, v127, v127
	global_store_short v179, v158, s[36:37]
	v_add_f32_e32 v111, v111, v159
	global_store_dword v178, v111, s[28:29] offset:128
	v_cvt_pk_bf16_f32 v159, v111, v111
	global_store_short v179, v159, s[36:37] offset:64
	v_add_u32_e32 v178, 0x40000, v176
	global_load_dword v128, v178, s[28:29]
	global_load_dword v129, v178, s[28:29] offset:128
	v_add_u32_e32 v178, 0x41000, v176
	global_load_dword v130, v178, s[28:29]
	global_load_dword v131, v178, s[28:29] offset:128
	v_add_u32_e32 v178, 0x42000, v176
	global_load_dword v132, v178, s[28:29]
	global_load_dword v133, v178, s[28:29] offset:128
	v_add_u32_e32 v178, 0x43000, v176
	global_load_dword v134, v178, s[28:29]
	global_load_dword v135, v178, s[28:29] offset:128
	v_add_u32_e32 v178, 0x48000, v176
	global_load_dword v136, v178, s[28:29]
	global_load_dword v137, v178, s[28:29] offset:128
	v_add_u32_e32 v178, 0x49000, v176
	global_load_dword v138, v178, s[28:29]
	global_load_dword v139, v178, s[28:29] offset:128
	v_add_u32_e32 v178, 0x4a000, v176
	global_load_dword v140, v178, s[28:29]
	global_load_dword v141, v178, s[28:29] offset:128
	v_add_u32_e32 v178, 0x4b000, v176
	global_load_dword v142, v178, s[28:29]
	global_load_dword v143, v178, s[28:29] offset:128
	v_add_u32_e32 v178, 0x50000, v176
	global_load_dword v144, v178, s[28:29]
	global_load_dword v145, v178, s[28:29] offset:128
	v_add_u32_e32 v178, 0x51000, v176
	global_load_dword v146, v178, s[28:29]
	global_load_dword v147, v178, s[28:29] offset:128
	v_add_u32_e32 v178, 0x52000, v176
	global_load_dword v148, v178, s[28:29]
	global_load_dword v149, v178, s[28:29] offset:128
	v_add_u32_e32 v178, 0x53000, v176
	global_load_dword v150, v178, s[28:29]
	global_load_dword v151, v178, s[28:29] offset:128
	v_add_u32_e32 v178, 0x58000, v176
	global_load_dword v152, v178, s[28:29]
	global_load_dword v153, v178, s[28:29] offset:128
	v_add_u32_e32 v178, 0x59000, v176
	global_load_dword v154, v178, s[28:29]
	global_load_dword v155, v178, s[28:29] offset:128
	v_add_u32_e32 v178, 0x5a000, v176
	global_load_dword v156, v178, s[28:29]
	global_load_dword v157, v178, s[28:29] offset:128
	v_add_u32_e32 v178, 0x5b000, v176
	global_load_dword v158, v178, s[28:29]
	global_load_dword v159, v178, s[28:29] offset:128
	s_waitcnt vmcnt(63)
	v_add_u32_e32 v178, 0x20000, v176
	v_add_u32_e32 v179, 0x10000, v177
	v_add_f32_e32 v80, v80, v160
	global_store_dword v178, v80, s[28:29]
	v_cvt_pk_bf16_f32 v160, v80, v80
	global_store_short v179, v160, s[36:37]
	v_add_f32_e32 v64, v64, v161
	global_store_dword v178, v64, s[28:29] offset:128
	v_cvt_pk_bf16_f32 v161, v64, v64
	global_store_short v179, v161, s[36:37] offset:64
	v_add_u32_e32 v178, 0x21000, v176
	v_add_u32_e32 v179, 0x10800, v177
	v_add_f32_e32 v81, v81, v162
	global_store_dword v178, v81, s[28:29]
	v_cvt_pk_bf16_f32 v162, v81, v81
	global_store_short v179, v162, s[36:37]
	v_add_f32_e32 v65, v65, v163
	global_store_dword v178, v65, s[28:29] offset:128
	v_cvt_pk_bf16_f32 v163, v65, v65
	global_store_short v179, v163, s[36:37] offset:64
	v_add_u32_e32 v178, 0x22000, v176
	v_add_u32_e32 v179, 0x11000, v177
	v_add_f32_e32 v82, v82, v164
	global_store_dword v178, v82, s[28:29]
	v_cvt_pk_bf16_f32 v164, v82, v82
	global_store_short v179, v164, s[36:37]
	v_add_f32_e32 v66, v66, v165
	global_store_dword v178, v66, s[28:29] offset:128
	v_cvt_pk_bf16_f32 v165, v66, v66
	global_store_short v179, v165, s[36:37] offset:64
	v_add_u32_e32 v178, 0x23000, v176
	v_add_u32_e32 v179, 0x11800, v177
	v_add_f32_e32 v83, v83, v166
	global_store_dword v178, v83, s[28:29]
	v_cvt_pk_bf16_f32 v166, v83, v83
	global_store_short v179, v166, s[36:37]
	v_add_f32_e32 v67, v67, v167
	global_store_dword v178, v67, s[28:29] offset:128
	v_cvt_pk_bf16_f32 v167, v67, v67
	global_store_short v179, v167, s[36:37] offset:64
	v_add_u32_e32 v178, 0x28000, v176
	v_add_u32_e32 v179, 0x14000, v177
	v_add_f32_e32 v84, v84, v168
	global_store_dword v178, v84, s[28:29]
	v_cvt_pk_bf16_f32 v168, v84, v84
	global_store_short v179, v168, s[36:37]
	v_add_f32_e32 v68, v68, v169
	global_store_dword v178, v68, s[28:29] offset:128
	v_cvt_pk_bf16_f32 v169, v68, v68
	global_store_short v179, v169, s[36:37] offset:64
	v_add_u32_e32 v178, 0x29000, v176
	v_add_u32_e32 v179, 0x14800, v177
	v_add_f32_e32 v85, v85, v170
	global_store_dword v178, v85, s[28:29]
	v_cvt_pk_bf16_f32 v170, v85, v85
	global_store_short v179, v170, s[36:37]
	v_add_f32_e32 v69, v69, v171
	global_store_dword v178, v69, s[28:29] offset:128
	v_cvt_pk_bf16_f32 v171, v69, v69
	global_store_short v179, v171, s[36:37] offset:64
	v_add_u32_e32 v178, 0x2a000, v176
	v_add_u32_e32 v179, 0x15000, v177
	v_add_f32_e32 v86, v86, v172
	global_store_dword v178, v86, s[28:29]
	v_cvt_pk_bf16_f32 v172, v86, v86
	global_store_short v179, v172, s[36:37]
	v_add_f32_e32 v70, v70, v173
	global_store_dword v178, v70, s[28:29] offset:128
	v_cvt_pk_bf16_f32 v173, v70, v70
	global_store_short v179, v173, s[36:37] offset:64
	v_add_u32_e32 v178, 0x2b000, v176
	v_add_u32_e32 v179, 0x15800, v177
	v_add_f32_e32 v87, v87, v174
	global_store_dword v178, v87, s[28:29]
	v_cvt_pk_bf16_f32 v174, v87, v87
	global_store_short v179, v174, s[36:37]
	v_add_f32_e32 v71, v71, v175
	global_store_dword v178, v71, s[28:29] offset:128
	v_cvt_pk_bf16_f32 v175, v71, v71
	global_store_short v179, v175, s[36:37] offset:64
	v_add_u32_e32 v178, 0x30000, v176
; DI void phase_resid(const Params& p, const bfu* A, int lda, const bfu* Bt, int K, char* smem) {
;     ...
;     EPI_BEGINM(acc, 4)
;       float* xp = p.out + (size_t)row * 1024 + col;
;       float nv = *xp + v; *xp = nv; p.xb[(size_t)row * 1024 + col] = f2bf(nv);
;     EPI_END
	v_add_u32_e32 v179, 0x18000, v177
	v_add_f32_e32 v88, v88, v184
	global_store_dword v178, v88, s[28:29]
	v_cvt_pk_bf16_f32 v184, v88, v88
	global_store_short v179, v184, s[36:37]
	v_add_f32_e32 v72, v72, v185
	global_store_dword v178, v72, s[28:29] offset:128
	v_cvt_pk_bf16_f32 v185, v72, v72
	global_store_short v179, v185, s[36:37] offset:64
	v_add_u32_e32 v178, 0x31000, v176
	v_add_u32_e32 v179, 0x18800, v177
	v_add_f32_e32 v89, v89, v186
	global_store_dword v178, v89, s[28:29]
	v_cvt_pk_bf16_f32 v186, v89, v89
	global_store_short v179, v186, s[36:37]
	v_add_f32_e32 v73, v73, v187
	global_store_dword v178, v73, s[28:29] offset:128
	v_cvt_pk_bf16_f32 v187, v73, v73
	global_store_short v179, v187, s[36:37] offset:64
	v_add_u32_e32 v178, 0x32000, v176
	v_add_u32_e32 v179, 0x19000, v177
	v_add_f32_e32 v90, v90, v190
	global_store_dword v178, v90, s[28:29]
	v_cvt_pk_bf16_f32 v190, v90, v90
	global_store_short v179, v190, s[36:37]
	v_add_f32_e32 v74, v74, v191
	global_store_dword v178, v74, s[28:29] offset:128
	v_cvt_pk_bf16_f32 v191, v74, v74
	global_store_short v179, v191, s[36:37] offset:64
	v_add_u32_e32 v178, 0x33000, v176
	v_add_u32_e32 v179, 0x19800, v177
	v_add_f32_e32 v91, v91, v192
	global_store_dword v178, v91, s[28:29]
	v_cvt_pk_bf16_f32 v192, v91, v91
	global_store_short v179, v192, s[36:37]
	v_add_f32_e32 v75, v75, v193
	global_store_dword v178, v75, s[28:29] offset:128
	v_cvt_pk_bf16_f32 v193, v75, v75
	global_store_short v179, v193, s[36:37] offset:64
	v_add_u32_e32 v178, 0x38000, v176
	v_add_u32_e32 v179, 0x1c000, v177
	v_add_f32_e32 v92, v92, v194
	global_store_dword v178, v92, s[28:29]
	v_cvt_pk_bf16_f32 v194, v92, v92
	global_store_short v179, v194, s[36:37]
	v_add_f32_e32 v76, v76, v195
	global_store_dword v178, v76, s[28:29] offset:128
	v_cvt_pk_bf16_f32 v195, v76, v76
	global_store_short v179, v195, s[36:37] offset:64
	v_add_u32_e32 v178, 0x39000, v176
	v_add_u32_e32 v179, 0x1c800, v177
	v_add_f32_e32 v93, v93, v196
	global_store_dword v178, v93, s[28:29]
	v_cvt_pk_bf16_f32 v196, v93, v93
	global_store_short v179, v196, s[36:37]
	v_add_f32_e32 v77, v77, v197
	global_store_dword v178, v77, s[28:29] offset:128
	v_cvt_pk_bf16_f32 v197, v77, v77
	global_store_short v179, v197, s[36:37] offset:64
	v_add_u32_e32 v178, 0x3a000, v176
	v_add_u32_e32 v179, 0x1d000, v177
	v_add_f32_e32 v94, v94, v198
	global_store_dword v178, v94, s[28:29]
	v_cvt_pk_bf16_f32 v198, v94, v94
	global_store_short v179, v198, s[36:37]
	v_add_f32_e32 v78, v78, v199
	global_store_dword v178, v78, s[28:29] offset:128
	v_cvt_pk_bf16_f32 v199, v78, v78
	global_store_short v179, v199, s[36:37] offset:64
	v_add_u32_e32 v178, 0x3b000, v176
	v_add_u32_e32 v179, 0x1d800, v177
	v_add_f32_e32 v95, v95, v200
	global_store_dword v178, v95, s[28:29]
	v_cvt_pk_bf16_f32 v200, v95, v95
	global_store_short v179, v200, s[36:37]
	v_add_f32_e32 v79, v79, v201
	global_store_dword v178, v79, s[28:29] offset:128
	v_cvt_pk_bf16_f32 v201, v79, v79
	global_store_short v179, v201, s[36:37] offset:64
	v_add_u32_e32 v178, 0x60000, v176
	global_load_dword v160, v178, s[28:29]
	global_load_dword v161, v178, s[28:29] offset:128
	v_add_u32_e32 v178, 0x61000, v176
	global_load_dword v162, v178, s[28:29]
	global_load_dword v163, v178, s[28:29] offset:128
	v_add_u32_e32 v178, 0x62000, v176
	global_load_dword v164, v178, s[28:29]
	global_load_dword v165, v178, s[28:29] offset:128
	v_add_u32_e32 v178, 0x63000, v176
	global_load_dword v166, v178, s[28:29]
	global_load_dword v167, v178, s[28:29] offset:128
	v_add_u32_e32 v178, 0x68000, v176
	global_load_dword v168, v178, s[28:29]
	global_load_dword v169, v178, s[28:29] offset:128
	v_add_u32_e32 v178, 0x69000, v176
	global_load_dword v170, v178, s[28:29]
	global_load_dword v171, v178, s[28:29] offset:128
	v_add_u32_e32 v178, 0x6a000, v176
	global_load_dword v172, v178, s[28:29]
	global_load_dword v173, v178, s[28:29] offset:128
	v_add_u32_e32 v178, 0x6b000, v176
	global_load_dword v174, v178, s[28:29]
	global_load_dword v175, v178, s[28:29] offset:128
	v_add_u32_e32 v178, 0x70000, v176
	global_load_dword v184, v178, s[28:29]
	global_load_dword v185, v178, s[28:29] offset:128
	v_add_u32_e32 v178, 0x71000, v176
	global_load_dword v186, v178, s[28:29]
	global_load_dword v187, v178, s[28:29] offset:128
	v_add_u32_e32 v178, 0x72000, v176
	global_load_dword v190, v178, s[28:29]
	global_load_dword v191, v178, s[28:29] offset:128
	v_add_u32_e32 v178, 0x73000, v176
	global_load_dword v192, v178, s[28:29]
	global_load_dword v193, v178, s[28:29] offset:128
	v_add_u32_e32 v178, 0x78000, v176
	global_load_dword v194, v178, s[28:29]
	global_load_dword v195, v178, s[28:29] offset:128
	v_add_u32_e32 v178, 0x79000, v176
	global_load_dword v196, v178, s[28:29]
	global_load_dword v197, v178, s[28:29] offset:128
	v_add_u32_e32 v178, 0x7a000, v176
	global_load_dword v198, v178, s[28:29]
	global_load_dword v199, v178, s[28:29] offset:128
	v_add_u32_e32 v178, 0x7b000, v176
	global_load_dword v200, v178, s[28:29]
	global_load_dword v201, v178, s[28:29] offset:128
	s_waitcnt vmcnt(63)
; DI void phase_resid(const Params& p, const bfu* A, int lda, const bfu* Bt, int K, char* smem) {
;     ...
;     EPI_BEGINM(acc, 4)
;       float* xp = p.out + (size_t)row * 1024 + col;
;       float nv = *xp + v; *xp = nv; p.xb[(size_t)row * 1024 + col] = f2bf(nv);
;     EPI_END
	v_add_u32_e32 v178, 0x40000, v176
	v_add_u32_e32 v179, 0x20000, v177
	v_add_f32_e32 v48, v48, v128
	global_store_dword v178, v48, s[28:29]
	v_cvt_pk_bf16_f32 v128, v48, v48
	global_store_short v179, v128, s[36:37]
	v_add_f32_e32 v32, v32, v129
	global_store_dword v178, v32, s[28:29] offset:128
	v_cvt_pk_bf16_f32 v129, v32, v32
	global_store_short v179, v129, s[36:37] offset:64
	v_add_u32_e32 v178, 0x41000, v176
	v_add_u32_e32 v179, 0x20800, v177
	v_add_f32_e32 v49, v49, v130
	global_store_dword v178, v49, s[28:29]
	v_cvt_pk_bf16_f32 v130, v49, v49
	global_store_short v179, v130, s[36:37]
	v_add_f32_e32 v33, v33, v131
	global_store_dword v178, v33, s[28:29] offset:128
	v_cvt_pk_bf16_f32 v131, v33, v33
	global_store_short v179, v131, s[36:37] offset:64
	v_add_u32_e32 v178, 0x42000, v176
	v_add_u32_e32 v179, 0x21000, v177
	v_add_f32_e32 v50, v50, v132
	global_store_dword v178, v50, s[28:29]
	v_cvt_pk_bf16_f32 v132, v50, v50
	global_store_short v179, v132, s[36:37]
	v_add_f32_e32 v34, v34, v133
	global_store_dword v178, v34, s[28:29] offset:128
	v_cvt_pk_bf16_f32 v133, v34, v34
	global_store_short v179, v133, s[36:37] offset:64
	v_add_u32_e32 v178, 0x43000, v176
	v_add_u32_e32 v179, 0x21800, v177
	v_add_f32_e32 v51, v51, v134
	global_store_dword v178, v51, s[28:29]
	v_cvt_pk_bf16_f32 v134, v51, v51
	global_store_short v179, v134, s[36:37]
	v_add_f32_e32 v35, v35, v135
	global_store_dword v178, v35, s[28:29] offset:128
	v_cvt_pk_bf16_f32 v135, v35, v35
	global_store_short v179, v135, s[36:37] offset:64
	v_add_u32_e32 v178, 0x48000, v176
	v_add_u32_e32 v179, 0x24000, v177
	v_add_f32_e32 v52, v52, v136
	global_store_dword v178, v52, s[28:29]
	v_cvt_pk_bf16_f32 v136, v52, v52
	global_store_short v179, v136, s[36:37]
	v_add_f32_e32 v36, v36, v137
	global_store_dword v178, v36, s[28:29] offset:128
	v_cvt_pk_bf16_f32 v137, v36, v36
	global_store_short v179, v137, s[36:37] offset:64
	v_add_u32_e32 v178, 0x49000, v176
	v_add_u32_e32 v179, 0x24800, v177
	v_add_f32_e32 v53, v53, v138
	global_store_dword v178, v53, s[28:29]
	v_cvt_pk_bf16_f32 v138, v53, v53
	global_store_short v179, v138, s[36:37]
	v_add_f32_e32 v37, v37, v139
	global_store_dword v178, v37, s[28:29] offset:128
	v_cvt_pk_bf16_f32 v139, v37, v37
	global_store_short v179, v139, s[36:37] offset:64
	v_add_u32_e32 v178, 0x4a000, v176
	v_add_u32_e32 v179, 0x25000, v177
	v_add_f32_e32 v54, v54, v140
	global_store_dword v178, v54, s[28:29]
	v_cvt_pk_bf16_f32 v140, v54, v54
	global_store_short v179, v140, s[36:37]
	v_add_f32_e32 v38, v38, v141
	global_store_dword v178, v38, s[28:29] offset:128
	v_cvt_pk_bf16_f32 v141, v38, v38
	global_store_short v179, v141, s[36:37] offset:64
	v_add_u32_e32 v178, 0x4b000, v176
	v_add_u32_e32 v179, 0x25800, v177
	v_add_f32_e32 v55, v55, v142
	global_store_dword v178, v55, s[28:29]
	v_cvt_pk_bf16_f32 v142, v55, v55
	global_store_short v179, v142, s[36:37]
	v_add_f32_e32 v39, v39, v143
	global_store_dword v178, v39, s[28:29] offset:128
	v_cvt_pk_bf16_f32 v143, v39, v39
	global_store_short v179, v143, s[36:37] offset:64
	v_add_u32_e32 v178, 0x50000, v176
	v_add_u32_e32 v179, 0x28000, v177
	v_add_f32_e32 v56, v56, v144
	global_store_dword v178, v56, s[28:29]
	v_cvt_pk_bf16_f32 v144, v56, v56
	global_store_short v179, v144, s[36:37]
	v_add_f32_e32 v40, v40, v145
	global_store_dword v178, v40, s[28:29] offset:128
	v_cvt_pk_bf16_f32 v145, v40, v40
	global_store_short v179, v145, s[36:37] offset:64
	v_add_u32_e32 v178, 0x51000, v176
	v_add_u32_e32 v179, 0x28800, v177
	v_add_f32_e32 v57, v57, v146
	global_store_dword v178, v57, s[28:29]
	v_cvt_pk_bf16_f32 v146, v57, v57
	global_store_short v179, v146, s[36:37]
	v_add_f32_e32 v41, v41, v147
	global_store_dword v178, v41, s[28:29] offset:128
	v_cvt_pk_bf16_f32 v147, v41, v41
	global_store_short v179, v147, s[36:37] offset:64
	v_add_u32_e32 v178, 0x52000, v176
	v_add_u32_e32 v179, 0x29000, v177
	v_add_f32_e32 v58, v58, v148
	global_store_dword v178, v58, s[28:29]
	v_cvt_pk_bf16_f32 v148, v58, v58
	global_store_short v179, v148, s[36:37]
	v_add_f32_e32 v42, v42, v149
	global_store_dword v178, v42, s[28:29] offset:128
	v_cvt_pk_bf16_f32 v149, v42, v42
	global_store_short v179, v149, s[36:37] offset:64
	v_add_u32_e32 v178, 0x53000, v176
	v_add_u32_e32 v179, 0x29800, v177
	v_add_f32_e32 v59, v59, v150
	global_store_dword v178, v59, s[28:29]
	v_cvt_pk_bf16_f32 v150, v59, v59
	global_store_short v179, v150, s[36:37]
	v_add_f32_e32 v43, v43, v151
	global_store_dword v178, v43, s[28:29] offset:128
	v_cvt_pk_bf16_f32 v151, v43, v43
	global_store_short v179, v151, s[36:37] offset:64
	v_add_u32_e32 v178, 0x58000, v176
	v_add_u32_e32 v179, 0x2c000, v177
	v_add_f32_e32 v60, v60, v152
	global_store_dword v178, v60, s[28:29]
	v_cvt_pk_bf16_f32 v152, v60, v60
	global_store_short v179, v152, s[36:37]
	v_add_f32_e32 v44, v44, v153
	global_store_dword v178, v44, s[28:29] offset:128
	v_cvt_pk_bf16_f32 v153, v44, v44
	global_store_short v179, v153, s[36:37] offset:64
	v_add_u32_e32 v178, 0x59000, v176
	v_add_u32_e32 v179, 0x2c800, v177
	v_add_f32_e32 v61, v61, v154
	global_store_dword v178, v61, s[28:29]
	v_cvt_pk_bf16_f32 v154, v61, v61
	global_store_short v179, v154, s[36:37]
	v_add_f32_e32 v45, v45, v155
	global_store_dword v178, v45, s[28:29] offset:128
	v_cvt_pk_bf16_f32 v155, v45, v45
	global_store_short v179, v155, s[36:37] offset:64
	v_add_u32_e32 v178, 0x5a000, v176
	v_add_u32_e32 v179, 0x2d000, v177
	v_add_f32_e32 v62, v62, v156
	global_store_dword v178, v62, s[28:29]
	v_cvt_pk_bf16_f32 v156, v62, v62
	global_store_short v179, v156, s[36:37]
	v_add_f32_e32 v46, v46, v157
	global_store_dword v178, v46, s[28:29] offset:128
	v_cvt_pk_bf16_f32 v157, v46, v46
	global_store_short v179, v157, s[36:37] offset:64
	v_add_u32_e32 v178, 0x5b000, v176
	v_add_u32_e32 v179, 0x2d800, v177
	v_add_f32_e32 v63, v63, v158
	global_store_dword v178, v63, s[28:29]
	v_cvt_pk_bf16_f32 v158, v63, v63
	global_store_short v179, v158, s[36:37]
	v_add_f32_e32 v47, v47, v159
	global_store_dword v178, v47, s[28:29] offset:128
	v_cvt_pk_bf16_f32 v159, v47, v47
	global_store_short v179, v159, s[36:37] offset:64
	s_waitcnt vmcnt(63)
; #define ZERO_ACCM(a, MT) _Pragma("unroll") for (int _m = 0; _m < MT; ++_m) _Pragma("unroll") for (int _n = 0; _n < 2; ++_n) _Pragma("unroll") for (int _i = 0; _i < 16; ++_i) a[_m][_n][_i] = 0.f;
; DI void phase_resid(const Params& p, const bfu* A, int lda, const bfu* Bt, int K, char* smem) {
;     ...
;   for (int id = blockIdx.x; id < 64 * 8; id += gridDim.x) {
;     int tm, tn; map_tile(id, 8, tm, tn);
;     const int m0 = tm * 256, n0 = tn * 128;
;     f32x16 acc[4][2]; ZERO_ACCM(acc, 4)
;     gemm_core<false, false, 4>(A, lda, Bt, K, K, m0, n0, acc, smem);
;     EPI_BEGINM(acc, 4)
;       float* xp = p.out + (size_t)row * 1024 + col;
;       float nv = *xp + v; *xp = nv; p.xb[(size_t)row * 1024 + col] = f2bf(nv);
;     EPI_END
	v_add_u32_e32 v178, 0x60000, v176
	v_add_u32_e32 v179, 0x30000, v177
	v_add_f32_e32 v16, v16, v160
	global_store_dword v178, v16, s[28:29]
	v_cvt_pk_bf16_f32 v160, v16, v16
	global_store_short v179, v160, s[36:37]
	v_add_f32_e32 v0, v0, v161
	global_store_dword v178, v0, s[28:29] offset:128
	v_cvt_pk_bf16_f32 v161, v0, v0
	global_store_short v179, v161, s[36:37] offset:64
	v_add_u32_e32 v178, 0x61000, v176
	v_add_u32_e32 v179, 0x30800, v177
	v_add_f32_e32 v17, v17, v162
	global_store_dword v178, v17, s[28:29]
	v_cvt_pk_bf16_f32 v162, v17, v17
	global_store_short v179, v162, s[36:37]
	v_add_f32_e32 v1, v1, v163
	global_store_dword v178, v1, s[28:29] offset:128
	v_cvt_pk_bf16_f32 v163, v1, v1
	global_store_short v179, v163, s[36:37] offset:64
	v_add_u32_e32 v178, 0x62000, v176
	v_add_u32_e32 v179, 0x31000, v177
	v_add_f32_e32 v18, v18, v164
	global_store_dword v178, v18, s[28:29]
	v_cvt_pk_bf16_f32 v164, v18, v18
	global_store_short v179, v164, s[36:37]
	v_add_f32_e32 v2, v2, v165
	global_store_dword v178, v2, s[28:29] offset:128
	v_cvt_pk_bf16_f32 v165, v2, v2
	global_store_short v179, v165, s[36:37] offset:64
	v_add_u32_e32 v178, 0x63000, v176
	v_add_u32_e32 v179, 0x31800, v177
	v_add_f32_e32 v19, v19, v166
	global_store_dword v178, v19, s[28:29]
	v_cvt_pk_bf16_f32 v166, v19, v19
	global_store_short v179, v166, s[36:37]
	v_add_f32_e32 v3, v3, v167
	global_store_dword v178, v3, s[28:29] offset:128
	v_cvt_pk_bf16_f32 v167, v3, v3
	global_store_short v179, v167, s[36:37] offset:64
	v_add_u32_e32 v178, 0x68000, v176
	v_add_u32_e32 v179, 0x34000, v177
	v_add_f32_e32 v20, v20, v168
	global_store_dword v178, v20, s[28:29]
	v_cvt_pk_bf16_f32 v168, v20, v20
	global_store_short v179, v168, s[36:37]
	v_add_f32_e32 v4, v4, v169
	global_store_dword v178, v4, s[28:29] offset:128
	v_cvt_pk_bf16_f32 v169, v4, v4
	global_store_short v179, v169, s[36:37] offset:64
	v_add_u32_e32 v178, 0x69000, v176
	v_add_u32_e32 v179, 0x34800, v177
	v_add_f32_e32 v21, v21, v170
	global_store_dword v178, v21, s[28:29]
	v_cvt_pk_bf16_f32 v170, v21, v21
	global_store_short v179, v170, s[36:37]
	v_add_f32_e32 v5, v5, v171
	global_store_dword v178, v5, s[28:29] offset:128
	v_cvt_pk_bf16_f32 v171, v5, v5
	global_store_short v179, v171, s[36:37] offset:64
	v_add_u32_e32 v178, 0x6a000, v176
	v_add_u32_e32 v179, 0x35000, v177
	v_add_f32_e32 v22, v22, v172
	global_store_dword v178, v22, s[28:29]
	v_cvt_pk_bf16_f32 v172, v22, v22
	global_store_short v179, v172, s[36:37]
	v_add_f32_e32 v6, v6, v173
	global_store_dword v178, v6, s[28:29] offset:128
	v_cvt_pk_bf16_f32 v173, v6, v6
	global_store_short v179, v173, s[36:37] offset:64
	v_add_u32_e32 v178, 0x6b000, v176
	v_add_u32_e32 v179, 0x35800, v177
	v_add_f32_e32 v23, v23, v174
	global_store_dword v178, v23, s[28:29]
	v_cvt_pk_bf16_f32 v174, v23, v23
	global_store_short v179, v174, s[36:37]
	v_add_f32_e32 v7, v7, v175
	global_store_dword v178, v7, s[28:29] offset:128
	v_cvt_pk_bf16_f32 v175, v7, v7
	global_store_short v179, v175, s[36:37] offset:64
	v_add_u32_e32 v178, 0x70000, v176
	v_add_u32_e32 v179, 0x38000, v177
	v_add_f32_e32 v24, v24, v184
	global_store_dword v178, v24, s[28:29]
	v_cvt_pk_bf16_f32 v184, v24, v24
	global_store_short v179, v184, s[36:37]
	v_add_f32_e32 v8, v8, v185
	global_store_dword v178, v8, s[28:29] offset:128
	v_cvt_pk_bf16_f32 v185, v8, v8
	global_store_short v179, v185, s[36:37] offset:64
	v_add_u32_e32 v178, 0x71000, v176
	v_add_u32_e32 v179, 0x38800, v177
	v_add_f32_e32 v25, v25, v186
	global_store_dword v178, v25, s[28:29]
	v_cvt_pk_bf16_f32 v186, v25, v25
	global_store_short v179, v186, s[36:37]
	v_add_f32_e32 v9, v9, v187
	global_store_dword v178, v9, s[28:29] offset:128
	v_cvt_pk_bf16_f32 v187, v9, v9
	global_store_short v179, v187, s[36:37] offset:64
	v_add_u32_e32 v178, 0x72000, v176
	v_add_u32_e32 v179, 0x39000, v177
	v_add_f32_e32 v26, v26, v190
	global_store_dword v178, v26, s[28:29]
	v_cvt_pk_bf16_f32 v190, v26, v26
	global_store_short v179, v190, s[36:37]
	v_add_f32_e32 v10, v10, v191
	global_store_dword v178, v10, s[28:29] offset:128
	v_cvt_pk_bf16_f32 v191, v10, v10
	global_store_short v179, v191, s[36:37] offset:64
	v_add_u32_e32 v178, 0x73000, v176
	v_add_u32_e32 v179, 0x39800, v177
	v_add_f32_e32 v27, v27, v192
	global_store_dword v178, v27, s[28:29]
	v_cvt_pk_bf16_f32 v192, v27, v27
	global_store_short v179, v192, s[36:37]
	v_add_f32_e32 v11, v11, v193
	global_store_dword v178, v11, s[28:29] offset:128
	v_cvt_pk_bf16_f32 v193, v11, v11
	global_store_short v179, v193, s[36:37] offset:64
	v_add_u32_e32 v178, 0x78000, v176
	v_add_u32_e32 v179, 0x3c000, v177
	v_add_f32_e32 v28, v28, v194
	global_store_dword v178, v28, s[28:29]
	v_cvt_pk_bf16_f32 v194, v28, v28
	global_store_short v179, v194, s[36:37]
	v_add_f32_e32 v12, v12, v195
	global_store_dword v178, v12, s[28:29] offset:128
	v_cvt_pk_bf16_f32 v195, v12, v12
	global_store_short v179, v195, s[36:37] offset:64
	v_add_u32_e32 v178, 0x79000, v176
	v_add_u32_e32 v179, 0x3c800, v177
	v_add_f32_e32 v29, v29, v196
	global_store_dword v178, v29, s[28:29]
	v_cvt_pk_bf16_f32 v196, v29, v29
	global_store_short v179, v196, s[36:37]
	v_add_f32_e32 v13, v13, v197
	global_store_dword v178, v13, s[28:29] offset:128
	v_cvt_pk_bf16_f32 v197, v13, v13
	global_store_short v179, v197, s[36:37] offset:64
	v_add_u32_e32 v178, 0x7a000, v176
	v_add_u32_e32 v179, 0x3d000, v177
	v_add_f32_e32 v30, v30, v198
	global_store_dword v178, v30, s[28:29]
	v_cvt_pk_bf16_f32 v198, v30, v30
	global_store_short v179, v198, s[36:37]
	v_add_f32_e32 v14, v14, v199
	global_store_dword v178, v14, s[28:29] offset:128
	v_cvt_pk_bf16_f32 v199, v14, v14
	global_store_short v179, v199, s[36:37] offset:64
	v_add_u32_e32 v178, 0x7b000, v176
	v_add_u32_e32 v179, 0x3d800, v177
	v_add_f32_e32 v31, v31, v200
	global_store_dword v178, v31, s[28:29]
	v_cvt_pk_bf16_f32 v200, v31, v31
	global_store_short v179, v200, s[36:37]
	v_add_f32_e32 v15, v15, v201
	global_store_dword v178, v15, s[28:29] offset:128
	v_cvt_pk_bf16_f32 v201, v15, v15
	global_store_short v179, v201, s[36:37] offset:64
	s_load_dword s3, s[4:5], 0x0
	s_waitcnt lgkmcnt(0)
	s_add_i32 s2, s3, s2
	s_cmpk_gt_i32 s2, 0x1ff
	s_cbranch_scc0 .LBB0_127

; DI int TID() { int t = threadIdx.x; asm volatile("" : "+v"(t)); return t; }
; DI void grid_barrier_light(unsigned* ctr, unsigned target) {
;   asm volatile("s_waitcnt vmcnt(0)" ::: "memory");
;   __syncthreads();
;   if (TID() == 0) {
;     __builtin_amdgcn_fence(__ATOMIC_RELEASE, "agent");
;     asm volatile("s_waitcnt vmcnt(0)" ::: "memory");
;     __hip_atomic_fetch_add(ctr, 1u, __ATOMIC_RELAXED, __HIP_MEMORY_SCOPE_AGENT);
;     while (__hip_atomic_load(ctr, __ATOMIC_RELAXED, __HIP_MEMORY_SCOPE_AGENT) < target) { }
;     __builtin_amdgcn_fence(__ATOMIC_ACQUIRE, "agent");
;     asm volatile("s_waitcnt vmcnt(0)" ::: "memory");
;   }
;   __syncthreads();
; }
.LBB0_2017:
	v_readlane_b32 s2, v255, 30
	s_add_i32 s10, s2, 1
	s_cmp_ge_i32 s10, s85
	v_readlane_b32 s8, v255, 22
	s_cbranch_scc1 .LBB0_2038
	v_readlane_b32 s2, v255, 30
	s_cmp_lg_u32 s2, s84
	s_mov_b64 s[2:3], -1
	s_cbranch_scc0 .LBB0_2026
	s_waitcnt vmcnt(0)
	v_readlane_b32 s2, v255, 22
	v_mov_b32_e32 v0, v224
	s_add_i32 s8, s2, 1
	s_waitcnt vmcnt(63) expcnt(7) lgkmcnt(15)
	s_barrier
	s_nop 0
	v_cmp_eq_u32_e32 vcc, 0, v0
	s_and_saveexec_b64 s[2:3], vcc
	s_cbranch_execz .LBB0_2025
	v_readlane_b32 s4, v254, 38
	v_readlane_b32 s5, v254, 39
	s_nop 3
	s_sub_u32 s4, s4, 0x288
	s_subb_u32 s5, s5, 0
	s_load_dwordx2 s[6:7], s[4:5], 0x250
	s_lshr_b32 s9, s100, 8
	s_cmp_lg_u32 s9, 0
	s_cbranch_scc1 .Lxb_ready
	s_load_dwordx2 s[4:5], s[4:5], 0x280
	v_mov_b32_e32 v1, 0
	s_waitcnt lgkmcnt(0)
	global_load_dword v4, v1, s[4:5] offset:32 sc1
	global_load_dword v5, v1, s[4:5] offset:36 sc1
	global_load_dword v6, v1, s[4:5] offset:40 sc1
	global_load_dword v7, v1, s[4:5] offset:44 sc1
	global_load_dword v8, v1, s[4:5] offset:48 sc1
	global_load_dword v9, v1, s[4:5] offset:52 sc1
	global_load_dword v10, v1, s[4:5] offset:56 sc1
	global_load_dword v11, v1, s[4:5] offset:60 sc1
	s_mov_b32 s14, 0
	s_mov_b32 s15, 1
	s_waitcnt vmcnt(0)
	v_readfirstlane_b32 s9, v4
	s_nop 3
	s_cmp_lg_u32 s9, 0
	s_addc_u32 s14, s14, 0
	s_cmp_eq_u32 s100, 0
	s_cselect_b32 s15, s9, s15
	v_readfirstlane_b32 s9, v5
	s_nop 3
	s_cmp_lg_u32 s9, 0
	s_addc_u32 s14, s14, 0
	s_cmp_eq_u32 s100, 1
	s_cselect_b32 s15, s9, s15
	v_readfirstlane_b32 s9, v6
	s_nop 3
	s_cmp_lg_u32 s9, 0
	s_addc_u32 s14, s14, 0
	s_cmp_eq_u32 s100, 2
	s_cselect_b32 s15, s9, s15
	v_readfirstlane_b32 s9, v7
	s_nop 3
	s_cmp_lg_u32 s9, 0
	s_addc_u32 s14, s14, 0
	s_cmp_eq_u32 s100, 3
	s_cselect_b32 s15, s9, s15
	v_readfirstlane_b32 s9, v8
	s_nop 3
	s_cmp_lg_u32 s9, 0
	s_addc_u32 s14, s14, 0
	s_cmp_eq_u32 s100, 4
	s_cselect_b32 s15, s9, s15
	v_readfirstlane_b32 s9, v9
	s_nop 3
	s_cmp_lg_u32 s9, 0
	s_addc_u32 s14, s14, 0
	s_cmp_eq_u32 s100, 5
	s_cselect_b32 s15, s9, s15
	v_readfirstlane_b32 s9, v10
	s_nop 3
	s_cmp_lg_u32 s9, 0
	s_addc_u32 s14, s14, 0
	s_cmp_eq_u32 s100, 6
	s_cselect_b32 s15, s9, s15
	v_readfirstlane_b32 s9, v11
	s_nop 3
	s_cmp_lg_u32 s9, 0
	s_addc_u32 s14, s14, 0
	s_cmp_eq_u32 s100, 7
	s_cselect_b32 s15, s9, s15
	s_lshl_b32 s15, s15, 8
	s_lshl_b32 s14, s14, 24
	s_or_b32 s100, s100, s15
	s_or_b32 s100, s100, s14
.Lxb_ready:
	s_waitcnt lgkmcnt(0)
	s_and_b32 s9, s100, 0xff
	s_lshl_b32 s9, s9, 8
	v_mov_b32_e32 v1, s9
	v_mov_b32_e32 v2, 1
	global_atomic_add v3, v1, v2, s[6:7] sc0
	s_bfe_u32 s14, s100, 0x100008
	s_mul_i32 s14, s14, s8
	s_add_u32 s9, s9, 0x800
	v_mov_b32_e32 v4, s9
	s_waitcnt vmcnt(0)
	v_readfirstlane_b32 s15, v3
	s_nop 3
	s_add_u32 s15, s15, 1
	s_cmp_eq_u32 s15, s14
	s_cbranch_scc0 .Lxb_follower
	buffer_wbl2 sc1
	s_waitcnt vmcnt(0)
	v_mov_b32_e32 v1, 0x1000
	global_atomic_add v3, v1, v2, s[6:7] sc0
	s_lshr_b32 s14, s100, 24
	s_mul_i32 s14, s14, s8
	v_mov_b32_e32 v1, 0x1100
	s_waitcnt vmcnt(0)
	v_readfirstlane_b32 s15, v3
	s_nop 3
	s_add_u32 s15, s15, 1
	s_cmp_eq_u32 s15, s14
	s_cbranch_scc0 .Lxb_top_wait
	global_atomic_add v1, v2, s[6:7]
	s_branch .Lxb_top_done
.Lxb_top_wait:
	s_mov_b32 s14, 0
.Lxb_top_spin:
	s_cmp_lg_u32 s101, 0
	s_cbranch_scc1 .Lxb_top_done
	s_sleep 1
	global_load_dword v3, v1, s[6:7] sc1
	s_add_u32 s14, s14, 1
	s_cmp_gt_u32 s14, 16384
	s_cselect_b32 s101, 1, s101
	s_waitcnt vmcnt(0)
	v_readfirstlane_b32 s15, v3
	s_nop 3
	s_cmp_lt_u32 s15, s8
	s_cbranch_scc1 .Lxb_top_spin
.Lxb_top_done:
	buffer_inv sc1
	global_atomic_add v4, v2, s[6:7]
	s_waitcnt vmcnt(0)
	s_branch .LBB0_2025

; DI int TID() { int t = threadIdx.x; asm volatile("" : "+v"(t)); return t; }
; DI void grid_barrier_light(unsigned* ctr, unsigned target) {
;   asm volatile("s_waitcnt vmcnt(0)" ::: "memory");
;   __syncthreads();
;   if (TID() == 0) {
;     __builtin_amdgcn_fence(__ATOMIC_RELEASE, "agent");
;     asm volatile("s_waitcnt vmcnt(0)" ::: "memory");
;     __hip_atomic_fetch_add(ctr, 1u, __ATOMIC_RELAXED, __HIP_MEMORY_SCOPE_AGENT);
;     while (__hip_atomic_load(ctr, __ATOMIC_RELAXED, __HIP_MEMORY_SCOPE_AGENT) < target) { }
;     __builtin_amdgcn_fence(__ATOMIC_ACQUIRE, "agent");
;     asm volatile("s_waitcnt vmcnt(0)" ::: "memory");
;   }
;   __syncthreads();
; }
.Lxb_f_spin:
	s_cmp_lg_u32 s101, 0
	s_cbranch_scc1 .Lxb_f_done
	s_sleep 1
	global_load_dword v3, v4, s[6:7] sc1
	s_add_u32 s14, s14, 1
	s_cmp_gt_u32 s14, 16384
	s_cselect_b32 s101, 1, s101
	s_waitcnt vmcnt(0)
	v_readfirstlane_b32 s15, v3
	s_nop 3
	s_cmp_lt_u32 s15, s8
	s_cbranch_scc1 .Lxb_f_spin
.Lxb_f_done:
	buffer_inv sc1
	s_waitcnt vmcnt(0)

; __global__ void __launch_bounds__(256, 2) hybrid_megakernel(Params p) {
;   __shared__ __attribute__((aligned(16))) char smem[SMEM_BYTES];
	.amdhsa_kernel _Z17hybrid_megakernel6Params
		.amdhsa_group_segment_fixed_size 61440
		.amdhsa_private_segment_fixed_size 0
		.amdhsa_kernarg_size 904
		.amdhsa_user_sgpr_count 2
		.amdhsa_user_sgpr_dispatch_ptr 0
		.amdhsa_user_sgpr_queue_ptr 0
		.amdhsa_user_sgpr_kernarg_segment_ptr 1
		.amdhsa_user_sgpr_dispatch_id 0
		.amdhsa_user_sgpr_kernarg_preload_length 0
		.amdhsa_user_sgpr_kernarg_preload_offset 0
		.amdhsa_user_sgpr_private_segment_size 0
		.amdhsa_uses_dynamic_stack 0
		.amdhsa_enable_private_segment 0
		.amdhsa_system_sgpr_workgroup_id_x 1
		.amdhsa_system_sgpr_workgroup_id_y 0
		.amdhsa_system_sgpr_workgroup_id_z 0
		.amdhsa_system_sgpr_workgroup_info 0
		.amdhsa_system_vgpr_workitem_id 2
		.amdhsa_next_free_vgpr 256
		.amdhsa_next_free_sgpr 102
		.amdhsa_accum_offset 256
		.amdhsa_reserve_vcc 1
		.amdhsa_float_round_mode_32 0
		.amdhsa_float_round_mode_16_64 0
		.amdhsa_float_denorm_mode_32 3
		.amdhsa_float_denorm_mode_16_64 3
		.amdhsa_dx10_clamp 1
		.amdhsa_ieee_mode 1
		.amdhsa_fp16_overflow 0
		.amdhsa_tg_split 0
		.amdhsa_exception_fp_ieee_invalid_op 0
		.amdhsa_exception_fp_denorm_src 0
		.amdhsa_exception_fp_ieee_div_zero 0
		.amdhsa_exception_fp_ieee_overflow 0
		.amdhsa_exception_fp_ieee_underflow 0
		.amdhsa_exception_fp_ieee_inexact 0
		.amdhsa_exception_int_div_zero 0
	.end_amdhsa_kernel

; __global__ void __launch_bounds__(256, 2) hybrid_megakernel(Params p) {
;   __shared__ __attribute__((aligned(16))) char smem[SMEM_BYTES];
amdhsa.kernels:
  - .agpr_count:     0
    .args:
      - .offset:         0
        .size:           648
        .value_kind:     by_value
      - .offset:         648
        .size:           4
        .value_kind:     hidden_block_count_x
      - .offset:         652
        .size:           4
        .value_kind:     hidden_block_count_y
      - .offset:         656
        .size:           4
        .value_kind:     hidden_block_count_z
      - .offset:         660
        .size:           2
        .value_kind:     hidden_group_size_x
      - .offset:         662
        .size:           2
        .value_kind:     hidden_group_size_y
      - .offset:         664
        .size:           2
        .value_kind:     hidden_group_size_z
      - .offset:         666
        .size:           2
        .value_kind:     hidden_remainder_x
      - .offset:         668
        .size:           2
        .value_kind:     hidden_remainder_y
      - .offset:         670
        .size:           2
        .value_kind:     hidden_remainder_z
      - .offset:         688
        .size:           8
        .value_kind:     hidden_global_offset_x
      - .offset:         696
        .size:           8
        .value_kind:     hidden_global_offset_y
      - .offset:         704
        .size:           8
        .value_kind:     hidden_global_offset_z
      - .offset:         712
        .size:           2
        .value_kind:     hidden_grid_dims
      - .offset:         736
        .size:           8
        .value_kind:     hidden_multigrid_sync_arg
    .group_segment_fixed_size: 61440
    .kernarg_segment_align: 8
    .kernarg_segment_size: 904
    .language:       OpenCL C
    .language_version:
      - 2
      - 0
    .max_flat_workgroup_size: 256
    .name:           _Z17hybrid_megakernel6Params
    .private_segment_fixed_size: 0
    .sgpr_count:     108
    .sgpr_spill_count: 179
    .symbol:         _Z17hybrid_megakernel6Params.kd
    .uniform_work_group_size: 1
    .uses_dynamic_stack: false
    .vgpr_count:     256
    .vgpr_spill_count: 0
    .wavefront_size: 64
